# back-edge rotation also on the remaining 5 GEMM k-loops (rotation only), on top of v_rot
# speedup vs baseline: 1.0065x; 1.0065x over previous
.LBB0_560:
	s_ashr_i32 s22, s30, 3
	s_lshr_b32 s24, s22, 29
	s_add_i32 s24, s22, s24
	s_and_b32 s25, s24, 0x1fffff8
	s_sub_i32 s22, s22, s25
	s_lshl_b32 s24, s24, 8
	s_lshl_b32 s25, s30, 8
	s_and_b32 s24, s24, 0xfffff800
	s_and_b32 s25, s25, 0x700
	s_or_b32 s28, s24, s25
	s_ashr_i32 s29, s28, 31
	s_lshl_b32 s24, s22, 7
	s_lshl_b64 s[34:35], s[28:29], 12
	s_add_u32 s34, s3, s34
	s_addc_u32 s35, s4, s35
	s_ashr_i32 s25, s24, 31
	v_mov_b32_e32 v36, v220
	s_lshl_b64 s[36:37], s[24:25], 12
	s_add_u32 s36, s5, s36
	v_ashrrev_i32_e32 v26, 2, v36
	v_ashrrev_i32_e32 v27, 31, v26
	s_addc_u32 s37, s8, s37
	v_lshlrev_b64 v[0:1], 12, v[26:27]
	v_lshlrev_b32_e32 v4, 4, v36
	v_lshl_add_u64 v[2:3], s[36:37], 0, v[0:1]
	v_lshl_add_u64 v[0:1], s[34:35], 0, v[0:1]
	v_and_b32_e32 v176, 48, v4
	s_waitcnt vmcnt(9)
	v_lshl_add_u64 v[152:153], v[0:1], 0, v[176:177]
	v_add_co_u32_e32 v28, vcc, s9, v152
	v_lshl_add_u64 v[154:155], v[2:3], 0, v[176:177]
	s_nop 0
	v_addc_co_u32_e32 v29, vcc, 0, v153, vcc
	v_add_co_u32_e32 v30, vcc, s26, v152
	global_load_dwordx4 v[2:5], v[152:153], off
	s_nop 0
	v_addc_co_u32_e32 v31, vcc, 0, v153, vcc
	v_add_co_u32_e32 v32, vcc, s27, v152
	global_load_dwordx4 v[6:9], v[28:29], off
	s_nop 0
	v_addc_co_u32_e32 v33, vcc, 0, v153, vcc
	v_add_co_u32_e32 v34, vcc, s9, v154
	global_load_dwordx4 v[10:13], v[30:31], off
	s_nop 0
	v_addc_co_u32_e32 v35, vcc, 0, v155, vcc
	global_load_dwordx4 v[14:17], v[32:33], off
	global_load_dwordx4 v[18:21], v[154:155], off
	global_load_dwordx4 v[22:25], v[34:35], off
	global_load_dwordx4 v[112:115], v[152:153], off offset:64
	global_load_dwordx4 v[120:123], v[28:29], off offset:64
	global_load_dwordx4 v[124:127], v[30:31], off offset:64
	global_load_dwordx4 v[128:131], v[32:33], off offset:64
	global_load_dwordx4 v[116:119], v[154:155], off offset:64
	global_load_dwordx4 v[132:135], v[34:35], off offset:64
	v_lshrrev_b32_e32 v27, 4, v36
	v_lshrrev_b32_e32 v37, 2, v36
	v_sub_u32_e32 v40, 0, v27
	v_sub_u32_e32 v37, 0, v37
	v_and_b32_e32 v38, 0x3ffff8f, v36
	v_lshlrev_b32_e32 v39, 6, v36
	v_xor_b32_e32 v36, v36, v40
	v_xor_b32_e32 v27, v27, v37
	v_lshlrev_b32_e32 v36, 4, v36
	v_lshlrev_b32_e32 v27, 4, v27
	v_and_b32_e32 v41, 0x1000, v39
	v_and_b32_e32 v36, 48, v36
	v_and_b32_e32 v27, 48, v27
	v_and_b32_e32 v42, 0x3c0, v39
	v_and_b32_e32 v39, 0xffffe3c0, v39
	v_lshl_add_u32 v38, v38, 6, v196
	v_lshl_or_b32 v164, v26, 6, v36
	v_or_b32_e32 v26, v27, v41
	s_mov_b32 s25, -2
	s_mov_b32 s29, s23
	v_mov_b32_e32 v0, 0
	v_mov_b32_e32 v1, v177
	v_or3_b32 v165, v41, v42, v27
	v_add_u32_e32 v166, v27, v39
	v_add_u32_e32 v167, v27, v38
	v_add_u32_e32 v168, v26, v42
	v_lshl_add_u64 v[156:157], v[152:153], 0, s[12:13]
	v_lshl_add_u64 v[158:159], v[152:153], 0, s[14:15]
	v_lshl_add_u64 v[160:161], v[152:153], 0, s[16:17]
	v_lshl_add_u64 v[162:163], v[154:155], 0, s[12:13]
	v_mov_b32_e32 v26, v177
	v_mov_b32_e32 v27, v177
	v_mov_b32_e32 v28, 0
	v_mov_b32_e32 v29, v177
	v_mov_b32_e32 v30, v177
	v_mov_b32_e32 v31, v177
	v_mov_b32_e32 v32, 0
	v_mov_b32_e32 v33, v177
	v_mov_b32_e32 v34, v177
	v_mov_b32_e32 v35, v177
	v_mov_b32_e32 v36, 0
	v_mov_b32_e32 v37, v177
	v_mov_b32_e32 v38, v177
	v_mov_b32_e32 v39, v177
	v_mov_b32_e32 v40, 0
	v_mov_b32_e32 v41, v177
	v_mov_b32_e32 v42, v177
	v_mov_b32_e32 v43, v177
	v_mov_b32_e32 v44, 0
	s_waitcnt vmcnt(11)
	ds_write_b128 v164, v[2:5]
	s_waitcnt vmcnt(10)
	ds_write_b128 v164, v[6:9] offset:4096
	s_waitcnt vmcnt(9)
	ds_write_b128 v164, v[10:13] offset:8192
	s_waitcnt vmcnt(8)
	ds_write_b128 v164, v[14:17] offset:12288
	s_waitcnt vmcnt(7)
	ds_write_b128 v164, v[18:21] offset:32768
	s_waitcnt vmcnt(6)
	ds_write_b128 v164, v[22:25] offset:36864
	v_mov_b32_e32 v2, v177
	v_mov_b32_e32 v3, v177
	v_mov_b32_e32 v4, 0
	v_mov_b32_e32 v5, v177
	v_mov_b32_e32 v6, v177
	v_mov_b32_e32 v7, v177
	v_mov_b32_e32 v8, 0
	v_mov_b32_e32 v9, v177
	v_mov_b32_e32 v10, v177
	v_mov_b32_e32 v11, v177
	v_mov_b32_e32 v12, 0
	v_mov_b32_e32 v13, v177
	v_mov_b32_e32 v14, v177
	v_mov_b32_e32 v15, v177
	v_mov_b32_e32 v16, 0
	v_mov_b32_e32 v17, v177
	v_mov_b32_e32 v18, v177
	v_mov_b32_e32 v19, v177
	v_mov_b32_e32 v20, 0
	v_mov_b32_e32 v21, v177
	v_mov_b32_e32 v22, v177
	v_mov_b32_e32 v23, v177
	v_mov_b32_e32 v24, 0
	v_mov_b32_e32 v25, v177
	v_mov_b32_e32 v45, v177
	v_mov_b32_e32 v46, v177
	v_mov_b32_e32 v47, v177
	v_mov_b32_e32 v48, 0
	v_mov_b32_e32 v49, v177
	v_mov_b32_e32 v50, v177
	v_mov_b32_e32 v51, v177
	v_mov_b32_e32 v52, 0
	v_mov_b32_e32 v53, v177
	v_mov_b32_e32 v54, v177
	v_mov_b32_e32 v55, v177
	v_mov_b32_e32 v56, 0
	v_mov_b32_e32 v57, v177
	v_mov_b32_e32 v58, v177
	v_mov_b32_e32 v59, v177
	v_mov_b32_e32 v60, 0
	v_mov_b32_e32 v61, v177
	v_mov_b32_e32 v62, v177
	v_mov_b32_e32 v63, v177
	v_mov_b32_e32 v64, 0
	v_mov_b32_e32 v65, v177
	v_mov_b32_e32 v66, v177
	v_mov_b32_e32 v67, v177
	v_mov_b32_e32 v68, 0
	v_mov_b32_e32 v69, v177
	v_mov_b32_e32 v70, v177
	v_mov_b32_e32 v71, v177
	v_mov_b32_e32 v72, 0
	v_mov_b32_e32 v73, v177
	v_mov_b32_e32 v74, v177
	v_mov_b32_e32 v75, v177
	v_mov_b32_e32 v76, 0
	v_mov_b32_e32 v77, v177
	v_mov_b32_e32 v78, v177
	v_mov_b32_e32 v79, v177
	v_mov_b32_e32 v80, 0
	v_mov_b32_e32 v81, v177
	v_mov_b32_e32 v82, v177
	v_mov_b32_e32 v83, v177
	v_mov_b32_e32 v84, 0
	v_mov_b32_e32 v85, v177
	v_mov_b32_e32 v86, v177
	v_mov_b32_e32 v87, v177
	v_mov_b32_e32 v88, 0
	v_mov_b32_e32 v89, v177
	v_mov_b32_e32 v90, v177
	v_mov_b32_e32 v91, v177
	v_mov_b32_e32 v92, 0
	v_mov_b32_e32 v93, v177
	v_mov_b32_e32 v94, v177
	v_mov_b32_e32 v95, v177
	v_mov_b32_e32 v96, 0
	v_mov_b32_e32 v97, v177
	v_mov_b32_e32 v98, v177
	v_mov_b32_e32 v99, v177
	v_mov_b32_e32 v100, 0
	v_mov_b32_e32 v101, v177
	v_mov_b32_e32 v102, v177
	v_mov_b32_e32 v103, v177
	v_mov_b32_e32 v104, 0
	v_mov_b32_e32 v105, v177
	v_mov_b32_e32 v106, v177
	v_mov_b32_e32 v107, v177
	v_mov_b32_e32 v108, 0
	v_mov_b32_e32 v109, v177
	v_mov_b32_e32 v110, v177
	v_mov_b32_e32 v111, v177
	v_mov_b32_e32 v136, 0
	v_mov_b32_e32 v137, v177
	v_mov_b32_e32 v138, v177
	v_mov_b32_e32 v139, v177
	v_mov_b32_e32 v140, 0
	v_mov_b32_e32 v141, v177
	v_mov_b32_e32 v142, v177
	v_mov_b32_e32 v143, v177
	v_mov_b32_e32 v144, 0
	v_mov_b32_e32 v145, v177
	v_mov_b32_e32 v146, v177
	v_mov_b32_e32 v147, v177
	v_mov_b32_e32 v148, 0
	v_mov_b32_e32 v149, v177
	v_mov_b32_e32 v150, v177
	v_mov_b32_e32 v151, v177
	s_waitcnt lgkmcnt(0)
.Lrot2_4:
	s_barrier
.LBB0_561:
	s_add_i32 s31, s29, 64
	s_min_u32 s22, s31, 0x7e0
	s_lshl_b32 s22, s22, 1
	v_lshl_add_u64 v[174:175], v[156:157], 0, s[22:23]
	global_load_dwordx4 v[178:181], v[174:175], off
	v_lshl_add_u64 v[174:175], v[158:159], 0, s[22:23]
	v_lshl_add_u64 v[170:171], v[152:153], 0, s[22:23]
	v_lshl_add_u64 v[186:187], v[160:161], 0, s[22:23]
	global_load_dwordx4 v[182:185], v[174:175], off
	v_lshl_add_u64 v[174:175], v[154:155], 0, s[22:23]
	v_lshl_add_u64 v[194:195], v[162:163], 0, s[22:23]
	global_load_dwordx4 v[170:173], v[170:171], off
	ds_read_b128 v[202:205], v168 offset:32768
	global_load_dwordx4 v[186:189], v[186:187], off
	ds_read_b128 v[206:209], v168 offset:33792
	global_load_dwordx4 v[190:193], v[174:175], off
	global_load_dwordx4 v[198:201], v[194:195], off
	ds_read_b128 v[210:213], v168 offset:34816
	ds_read_b128 v[214:217], v168 offset:35840
	ds_read_b128 v[222:225], v166
	ds_read_b128 v[226:229], v166 offset:1024
	ds_read_b128 v[230:233], v166 offset:2048
	ds_read_b128 v[234:237], v166 offset:3072
	ds_read_b128 v[238:241], v166 offset:4096
	ds_read_b128 v[242:245], v166 offset:5120
	ds_read_b128 v[246:249], v166 offset:6144
	ds_read_b128 v[250:253], v166 offset:7168
	s_setprio 1
	s_waitcnt lgkmcnt(7)
	v_mfma_f32_16x16x32_bf16 v[148:151], v[202:205], v[222:225], v[148:151]
	v_mfma_f32_16x16x32_bf16 v[144:147], v[206:209], v[222:225], v[144:147]
	v_mfma_f32_16x16x32_bf16 v[140:143], v[210:213], v[222:225], v[140:143]
	v_mfma_f32_16x16x32_bf16 v[136:139], v[214:217], v[222:225], v[136:139]
	s_waitcnt vmcnt(11)
	ds_write_b128 v164, v[112:115] offset:16384
	s_waitcnt lgkmcnt(7)
	v_mfma_f32_16x16x32_bf16 v[108:111], v[202:205], v[226:229], v[108:111]
	v_mfma_f32_16x16x32_bf16 v[104:107], v[206:209], v[226:229], v[104:107]
	v_mfma_f32_16x16x32_bf16 v[100:103], v[210:213], v[226:229], v[100:103]
	v_mfma_f32_16x16x32_bf16 v[96:99], v[214:217], v[226:229], v[96:99]
	s_waitcnt vmcnt(9)
	ds_write_b128 v164, v[120:123] offset:20480
	s_waitcnt lgkmcnt(7)
	v_mfma_f32_16x16x32_bf16 v[92:95], v[202:205], v[230:233], v[92:95]
	v_mfma_f32_16x16x32_bf16 v[88:91], v[206:209], v[230:233], v[88:91]
	v_mfma_f32_16x16x32_bf16 v[84:87], v[210:213], v[230:233], v[84:87]
	v_mfma_f32_16x16x32_bf16 v[80:83], v[214:217], v[230:233], v[80:83]
	s_waitcnt vmcnt(8)
	ds_write_b128 v164, v[124:127] offset:24576
	s_waitcnt lgkmcnt(7)
	v_mfma_f32_16x16x32_bf16 v[76:79], v[202:205], v[234:237], v[76:79]
	v_mfma_f32_16x16x32_bf16 v[72:75], v[206:209], v[234:237], v[72:75]
	v_mfma_f32_16x16x32_bf16 v[68:71], v[210:213], v[234:237], v[68:71]
	v_mfma_f32_16x16x32_bf16 v[64:67], v[214:217], v[234:237], v[64:67]
	s_waitcnt vmcnt(7)
	ds_write_b128 v164, v[128:131] offset:28672
	s_waitcnt lgkmcnt(7)
	v_mfma_f32_16x16x32_bf16 v[60:63], v[202:205], v[238:241], v[60:63]
	v_mfma_f32_16x16x32_bf16 v[56:59], v[206:209], v[238:241], v[56:59]
	v_mfma_f32_16x16x32_bf16 v[52:55], v[210:213], v[238:241], v[52:55]
	v_mfma_f32_16x16x32_bf16 v[48:51], v[214:217], v[238:241], v[48:51]
	s_waitcnt vmcnt(7)
	ds_write_b128 v164, v[116:119] offset:40960
	s_waitcnt lgkmcnt(7)
	v_mfma_f32_16x16x32_bf16 v[44:47], v[202:205], v[242:245], v[44:47]
	v_mfma_f32_16x16x32_bf16 v[40:43], v[206:209], v[242:245], v[40:43]
	v_mfma_f32_16x16x32_bf16 v[36:39], v[210:213], v[242:245], v[36:39]
	v_mfma_f32_16x16x32_bf16 v[32:35], v[214:217], v[242:245], v[32:35]
	s_waitcnt vmcnt(6)
	ds_write_b128 v164, v[132:135] offset:45056
	s_waitcnt lgkmcnt(7)
	v_mfma_f32_16x16x32_bf16 v[28:31], v[202:205], v[246:249], v[28:31]
	v_mfma_f32_16x16x32_bf16 v[24:27], v[206:209], v[246:249], v[24:27]
	v_mfma_f32_16x16x32_bf16 v[20:23], v[210:213], v[246:249], v[20:23]
	v_mfma_f32_16x16x32_bf16 v[16:19], v[214:217], v[246:249], v[16:19]
	s_waitcnt lgkmcnt(6)
	v_mfma_f32_16x16x32_bf16 v[12:15], v[202:205], v[250:253], v[12:15]
	v_mfma_f32_16x16x32_bf16 v[8:11], v[206:209], v[250:253], v[8:11]
	v_mfma_f32_16x16x32_bf16 v[4:7], v[210:213], v[250:253], v[4:7]
	v_mfma_f32_16x16x32_bf16 v[0:3], v[214:217], v[250:253], v[0:3]
	s_setprio 0
	s_min_u32 s22, s29, 0x780
	s_lshl_b32 s22, s22, 1
	s_mov_b32 s35, s23
	s_add_i32 s34, s22, 0xc0
	v_lshl_add_u64 v[112:113], v[152:153], 0, s[22:23]
	v_lshl_add_u64 v[116:117], v[154:155], 0, s[22:23]
	v_lshl_add_u64 v[120:121], v[156:157], 0, s[34:35]
	v_lshl_add_u64 v[124:125], v[158:159], 0, s[34:35]
	v_lshl_add_u64 v[128:129], v[160:161], 0, s[34:35]
	v_lshl_add_u64 v[132:133], v[162:163], 0, s[34:35]
	s_waitcnt lgkmcnt(0)
	s_barrier
	global_load_dwordx4 v[112:115], v[112:113], off offset:192
	ds_read_b128 v[202:205], v165 offset:40960
	global_load_dwordx4 v[116:119], v[116:117], off offset:192
	ds_read_b128 v[206:209], v165 offset:41984
	global_load_dwordx4 v[120:123], v[120:121], off
	ds_read_b128 v[210:213], v165 offset:43008
	global_load_dwordx4 v[124:127], v[124:125], off
	ds_read_b128 v[214:217], v165 offset:44032
	global_load_dwordx4 v[128:131], v[128:129], off
	ds_read_b128 v[222:225], v167
	global_load_dwordx4 v[132:135], v[132:133], off
	ds_read_b128 v[226:229], v167 offset:1024
	ds_read_b128 v[230:233], v167 offset:2048
	ds_read_b128 v[234:237], v167 offset:3072
	ds_read_b128 v[238:241], v167 offset:4096
	ds_read_b128 v[242:245], v167 offset:5120
	ds_read_b128 v[246:249], v167 offset:6144
	ds_read_b128 v[250:253], v167 offset:7168
	s_setprio 1
	s_waitcnt lgkmcnt(7)
	v_mfma_f32_16x16x32_bf16 v[148:151], v[202:205], v[222:225], v[148:151]
	v_mfma_f32_16x16x32_bf16 v[144:147], v[206:209], v[222:225], v[144:147]
	v_mfma_f32_16x16x32_bf16 v[140:143], v[210:213], v[222:225], v[140:143]
	v_mfma_f32_16x16x32_bf16 v[136:139], v[214:217], v[222:225], v[136:139]
	s_waitcnt vmcnt(9)
	ds_write_b128 v164, v[170:173]
	s_waitcnt lgkmcnt(7)
	v_mfma_f32_16x16x32_bf16 v[108:111], v[202:205], v[226:229], v[108:111]
	v_mfma_f32_16x16x32_bf16 v[104:107], v[206:209], v[226:229], v[104:107]
	v_mfma_f32_16x16x32_bf16 v[100:103], v[210:213], v[226:229], v[100:103]
	v_mfma_f32_16x16x32_bf16 v[96:99], v[214:217], v[226:229], v[96:99]
	ds_write_b128 v164, v[178:181] offset:4096
	s_waitcnt lgkmcnt(7)
	v_mfma_f32_16x16x32_bf16 v[92:95], v[202:205], v[230:233], v[92:95]
	v_mfma_f32_16x16x32_bf16 v[88:91], v[206:209], v[230:233], v[88:91]
	v_mfma_f32_16x16x32_bf16 v[84:87], v[210:213], v[230:233], v[84:87]
	v_mfma_f32_16x16x32_bf16 v[80:83], v[214:217], v[230:233], v[80:83]
	ds_write_b128 v164, v[182:185] offset:8192
	s_waitcnt lgkmcnt(7)
	v_mfma_f32_16x16x32_bf16 v[76:79], v[202:205], v[234:237], v[76:79]
	v_mfma_f32_16x16x32_bf16 v[72:75], v[206:209], v[234:237], v[72:75]
	v_mfma_f32_16x16x32_bf16 v[68:71], v[210:213], v[234:237], v[68:71]
	v_mfma_f32_16x16x32_bf16 v[64:67], v[214:217], v[234:237], v[64:67]
	s_waitcnt vmcnt(8)
	ds_write_b128 v164, v[186:189] offset:12288
	s_waitcnt lgkmcnt(7)
	v_mfma_f32_16x16x32_bf16 v[60:63], v[202:205], v[238:241], v[60:63]
	v_mfma_f32_16x16x32_bf16 v[56:59], v[206:209], v[238:241], v[56:59]
	v_mfma_f32_16x16x32_bf16 v[52:55], v[210:213], v[238:241], v[52:55]
	v_mfma_f32_16x16x32_bf16 v[48:51], v[214:217], v[238:241], v[48:51]
	s_waitcnt vmcnt(7)
	ds_write_b128 v164, v[190:193] offset:32768
	s_waitcnt lgkmcnt(7)
	v_mfma_f32_16x16x32_bf16 v[44:47], v[202:205], v[242:245], v[44:47]
	v_mfma_f32_16x16x32_bf16 v[40:43], v[206:209], v[242:245], v[40:43]
	v_mfma_f32_16x16x32_bf16 v[36:39], v[210:213], v[242:245], v[36:39]
	v_mfma_f32_16x16x32_bf16 v[32:35], v[214:217], v[242:245], v[32:35]
	s_waitcnt vmcnt(6)
	ds_write_b128 v164, v[198:201] offset:36864
	s_waitcnt lgkmcnt(7)
	v_mfma_f32_16x16x32_bf16 v[28:31], v[202:205], v[246:249], v[28:31]
	v_mfma_f32_16x16x32_bf16 v[24:27], v[206:209], v[246:249], v[24:27]
	v_mfma_f32_16x16x32_bf16 v[20:23], v[210:213], v[246:249], v[20:23]
	v_mfma_f32_16x16x32_bf16 v[16:19], v[214:217], v[246:249], v[16:19]
	s_waitcnt lgkmcnt(6)
	v_mfma_f32_16x16x32_bf16 v[12:15], v[202:205], v[250:253], v[12:15]
	v_mfma_f32_16x16x32_bf16 v[8:11], v[206:209], v[250:253], v[8:11]
	v_mfma_f32_16x16x32_bf16 v[4:7], v[210:213], v[250:253], v[4:7]
	v_mfma_f32_16x16x32_bf16 v[0:3], v[214:217], v[250:253], v[0:3]
	s_setprio 0
	s_add_i32 s25, s25, 2
	s_cmp_lt_u32 s25, 62
	s_mov_b32 s29, s31
	s_waitcnt lgkmcnt(0)
	s_cbranch_scc1 .Lrot2_4
	s_barrier
	s_waitcnt vmcnt(5)
	v_mov_b32_e32 v112, v220
	v_readlane_b32 s36, v254, 6
	v_and_b32_e32 v114, 0xffffff80, v112
	v_bfe_u32 v176, v112, 4, 2
	v_add_u32_e32 v114, s28, v114
	v_and_b32_e32 v113, 64, v112
	v_and_or_b32 v180, v112, 15, v114
	v_lshlrev_b32_e32 v112, 2, v176
	v_or3_b32 v178, v112, v113, s24
	v_ashrrev_i32_e32 v179, 31, v178
	v_lshlrev_b64 v[214:215], 2, v[178:179]
	v_readlane_b32 s37, v254, 7
	v_ashrrev_i32_e32 v181, 31, v180
	v_or_b32_e32 v190, 16, v180
	v_lshl_add_u64 v[182:183], s[36:37], 0, v[214:215]
	v_lshlrev_b64 v[216:217], 12, v[180:181]
	v_ashrrev_i32_e32 v191, 31, v190
	v_or_b32_e32 v186, 32, v180
	v_lshl_add_u64 v[112:113], v[182:183], 0, v[216:217]
	v_lshlrev_b64 v[194:195], 12, v[190:191]
	v_ashrrev_i32_e32 v187, 31, v186
	v_or_b32_e32 v184, 48, v180
	global_load_dwordx4 v[198:201], v[112:113], off nt
	global_load_dwordx4 v[202:205], v[112:113], off offset:64 nt
	global_load_dwordx4 v[206:209], v[112:113], off offset:128 nt
	global_load_dwordx4 v[210:213], v[112:113], off offset:192 nt
	v_lshl_add_u64 v[112:113], v[182:183], 0, v[194:195]
	v_lshlrev_b64 v[192:193], 12, v[186:187]
	v_ashrrev_i32_e32 v185, 31, v184
	global_load_dwordx4 v[172:175], v[112:113], off nt
	global_load_dwordx4 v[168:171], v[112:113], off offset:64 nt
	global_load_dwordx4 v[164:167], v[112:113], off offset:128 nt
	global_load_dwordx4 v[160:163], v[112:113], off offset:192 nt
	v_lshl_add_u64 v[112:113], v[182:183], 0, v[192:193]
	v_lshlrev_b64 v[188:189], 12, v[184:185]
	global_load_dwordx4 v[156:159], v[112:113], off nt
	global_load_dwordx4 v[152:155], v[112:113], off offset:64 nt
	global_load_dwordx4 v[132:135], v[112:113], off offset:128 nt
	global_load_dwordx4 v[128:131], v[112:113], off offset:192 nt
	v_lshl_add_u64 v[112:113], v[182:183], 0, v[188:189]
	global_load_dwordx4 v[124:127], v[112:113], off nt
	global_load_dwordx4 v[120:123], v[112:113], off offset:64 nt
	global_load_dwordx4 v[116:119], v[112:113], off offset:128 nt
	s_nop 0
	global_load_dwordx4 v[112:115], v[112:113], off offset:192 nt
	v_cmp_eq_u32_e32 vcc, 0, v176
	v_readlane_b32 s38, v254, 8
	v_readlane_b32 s39, v254, 9
	v_readlane_b32 s40, v254, 10
	v_readlane_b32 s41, v254, 11
	v_readlane_b32 s42, v254, 12
	v_readlane_b32 s43, v254, 13
	v_readlane_b32 s44, v254, 14
	v_readlane_b32 s45, v254, 15
	v_readlane_b32 s46, v254, 16
	v_readlane_b32 s47, v254, 17
	v_readlane_b32 s48, v254, 18
	v_readlane_b32 s49, v254, 19
	v_readlane_b32 s50, v254, 20
	v_readlane_b32 s51, v254, 21
	v_lshl_add_u64 v[216:217], s[70:71], 0, v[216:217]
	s_waitcnt vmcnt(15)
	v_pk_add_f32 v[148:149], v[148:149], v[198:199]
	v_lshl_add_u64 v[214:215], v[216:217], 0, v[214:215]
	v_pk_add_f32 v[150:151], v[150:151], v[200:201]
	v_mul_f32_e32 v176, v149, v149
	global_store_dwordx4 v[214:215], v[148:151], off
	v_cvt_pk_bf16_f32 v198, v148, v149
	v_lshlrev_b64 v[200:201], 11, v[180:181]
	v_cvt_pk_bf16_f32 v199, v150, v151
	v_lshl_add_u64 v[200:201], s[6:7], 0, v[200:201]
	v_pk_fma_f32 v[148:149], v[148:149], v[148:149], v[176:177] op_sel_hi:[1,1,0]
	v_lshl_add_u64 v[200:201], v[178:179], 1, v[200:201]
	v_pk_fma_f32 v[148:149], v[150:151], v[150:151], v[148:149]
	v_mul_f32_e32 v150, v151, v151
	v_pk_add_f32 v[148:149], v[150:151], v[148:149] op_sel_hi:[0,1]
	s_waitcnt vmcnt(15)
	v_pk_add_f32 v[146:147], v[146:147], v[204:205]
	v_pk_add_f32 v[144:145], v[144:145], v[202:203]
	global_store_dwordx2 v[200:201], v[198:199], off
	v_cvt_pk_bf16_f32 v150, v144, v145
	global_store_dwordx4 v[214:215], v[144:147], off offset:64
	v_cvt_pk_bf16_f32 v151, v146, v147
	global_store_dwordx2 v[200:201], v[150:151], off offset:32
	v_mul_f32_e32 v150, v145, v145
	v_pk_fma_f32 v[144:145], v[144:145], v[144:145], v[150:151] op_sel_hi:[1,1,0]
	s_waitcnt vmcnt(17)
	v_pk_add_f32 v[142:143], v[142:143], v[208:209]
	v_pk_fma_f32 v[144:145], v[146:147], v[146:147], v[144:145]
	v_mul_f32_e32 v146, v147, v147
	v_pk_add_f32 v[144:145], v[146:147], v[144:145] op_sel_hi:[0,1]
	v_pk_add_f32 v[140:141], v[140:141], v[206:207]
	global_store_dwordx4 v[214:215], v[140:143], off offset:128
	v_cvt_pk_bf16_f32 v146, v140, v141
	v_cvt_pk_bf16_f32 v147, v142, v143
	global_store_dwordx2 v[200:201], v[146:147], off offset:64
	v_mul_f32_e32 v146, v141, v141
	v_pk_fma_f32 v[140:141], v[140:141], v[140:141], v[146:147] op_sel_hi:[1,1,0]
	s_waitcnt vmcnt(18)
	v_pk_add_f32 v[138:139], v[138:139], v[212:213]
	v_pk_fma_f32 v[140:141], v[142:143], v[142:143], v[140:141]
	v_mul_f32_e32 v142, v143, v143
	v_pk_add_f32 v[140:141], v[142:143], v[140:141] op_sel_hi:[0,1]
	v_pk_add_f32 v[136:137], v[136:137], v[210:211]
	global_store_dwordx4 v[214:215], v[136:139], off offset:192
	v_cvt_pk_bf16_f32 v142, v136, v137
	v_cvt_pk_bf16_f32 v143, v138, v139
	global_store_dwordx2 v[200:201], v[142:143], off offset:96
	v_mul_f32_e32 v142, v137, v137
	v_pk_fma_f32 v[136:137], v[136:137], v[136:137], v[142:143] op_sel_hi:[1,1,0]
	v_pk_add_f32 v[144:145], v[148:149], v[144:145]
	v_pk_fma_f32 v[136:137], v[138:139], v[138:139], v[136:137]
	v_mul_f32_e32 v138, v139, v139
	v_pk_add_f32 v[140:141], v[144:145], v[140:141]
	v_pk_add_f32 v[136:137], v[138:139], v[136:137] op_sel_hi:[0,1]
	v_pk_add_f32 v[136:137], v[140:141], v[136:137]
	s_nop 0
	v_mov_b32_e32 v137, v136
	s_nop 1
	v_permlane32_swap_b32_e32 v136, v137
	v_add_f32_e32 v136, v136, v137
	v_mov_b32_e32 v137, v136
	s_nop 1
	v_permlane16_swap_b32_e32 v136, v137
	s_and_saveexec_b64 s[24:25], vcc
	s_cbranch_execz .LBB0_564
	v_lshl_add_u64 v[138:139], v[180:181], 2, s[10:11]
	v_add_f32_e32 v136, v136, v137
	global_atomic_add_f32 v[138:139], v136, off

.LBB0_634:
	s_min_u32 s31, s29, 0xe0
	s_lshl_b32 s16, s31, 2
	v_lshl_add_u64 v[58:59], v[42:43], 0, s[16:17]
	v_lshl_add_u64 v[92:93], v[48:49], 0, s[16:17]
	s_lshl_b32 s16, s31, 1
	global_load_dwordx4 v[64:67], v[58:59], off offset:16 nt
	global_load_dwordx4 v[68:71], v[58:59], off nt
	v_lshl_add_u64 v[58:59], v[34:35], 0, s[16:17]
	v_lshl_add_u64 v[100:101], v[40:41], 0, s[16:17]
	global_load_dwordx4 v[88:91], v[92:93], off offset:16 nt
	global_load_dwordx4 v[96:99], v[58:59], off
	s_and_b32 s16, s30, 0x80
	global_load_dwordx4 v[92:95], v[92:93], off nt
	v_add_u32_e32 v57, s16, v50
	global_load_dwordx4 v[100:103], v[100:101], off
	v_or_b32_e32 v58, s16, v56
	v_lshl_or_b32 v57, v57, 6, v51
	v_lshl_or_b32 v58, v58, 6, v51
	ds_read_b128 v[104:107], v57
	ds_read_b128 v[108:111], v57 offset:1024
	ds_read_b128 v[112:115], v58 offset:16384
	ds_read_b128 v[116:119], v58 offset:17408
	ds_read_b128 v[120:123], v57 offset:2048
	ds_read_b128 v[124:127], v57 offset:3072
	ds_read_b128 v[128:131], v58 offset:18432
	ds_read_b128 v[132:135], v58 offset:19456
	s_setprio 1
	s_waitcnt lgkmcnt(5)
	v_mfma_f32_16x16x32_bf16 v[84:87], v[112:115], v[104:107], v[84:87]
	s_waitcnt lgkmcnt(4)
	v_mfma_f32_16x16x32_bf16 v[80:83], v[116:119], v[104:107], v[80:83]
	s_waitcnt lgkmcnt(1)
	v_mfma_f32_16x16x32_bf16 v[76:79], v[128:131], v[104:107], v[76:79]
	s_waitcnt lgkmcnt(0)
	v_mfma_f32_16x16x32_bf16 v[72:75], v[132:135], v[104:107], v[72:75]
	v_mfma_f32_16x16x32_bf16 v[60:63], v[112:115], v[108:111], v[60:63]
	v_mfma_f32_16x16x32_bf16 v[52:55], v[116:119], v[108:111], v[52:55]
	v_mfma_f32_16x16x32_bf16 v[44:47], v[128:131], v[108:111], v[44:47]
	v_mfma_f32_16x16x32_bf16 v[36:39], v[132:135], v[108:111], v[36:39]
	v_mfma_f32_16x16x32_bf16 v[28:31], v[112:115], v[120:123], v[28:31]
	v_mfma_f32_16x16x32_bf16 v[24:27], v[116:119], v[120:123], v[24:27]
	v_mfma_f32_16x16x32_bf16 v[20:23], v[128:131], v[120:123], v[20:23]
	v_mfma_f32_16x16x32_bf16 v[16:19], v[132:135], v[120:123], v[16:19]
	v_mfma_f32_16x16x32_bf16 v[12:15], v[112:115], v[124:127], v[12:15]
	v_mfma_f32_16x16x32_bf16 v[8:11], v[116:119], v[124:127], v[8:11]
	v_mfma_f32_16x16x32_bf16 v[4:7], v[128:131], v[124:127], v[4:7]
	v_mfma_f32_16x16x32_bf16 v[0:3], v[132:135], v[124:127], v[0:3]
	s_setprio 0
	s_waitcnt vmcnt(4)
	v_and_b32_sdwa v58, v70, v199 dst_sel:DWORD dst_unused:UNUSED_PAD src0_sel:WORD_1 src1_sel:DWORD
	v_and_b32_sdwa v59, v68, v199 dst_sel:DWORD dst_unused:UNUSED_PAD src0_sel:WORD_1 src1_sel:DWORD
	v_add3_u32 v59, v68, v59, s9
	v_add3_u32 v58, v70, v58, s9
	v_and_b32_sdwa v68, v71, v199 dst_sel:DWORD dst_unused:UNUSED_PAD src0_sel:WORD_1 src1_sel:DWORD
	v_and_b32_sdwa v70, v69, v199 dst_sel:DWORD dst_unused:UNUSED_PAD src0_sel:WORD_1 src1_sel:DWORD
	v_add3_u32 v68, v71, v68, s9
	v_add3_u32 v69, v69, v70, s9
	v_and_b32_e32 v68, 0xffff0000, v68
	v_and_b32_e32 v70, 0xffff0000, v69
	v_or_b32_sdwa v69, v68, v58 dst_sel:DWORD dst_unused:UNUSED_PAD src0_sel:DWORD src1_sel:WORD_1
	v_or_b32_sdwa v68, v70, v59 dst_sel:DWORD dst_unused:UNUSED_PAD src0_sel:DWORD src1_sel:WORD_1
	v_and_b32_sdwa v58, v66, v199 dst_sel:DWORD dst_unused:UNUSED_PAD src0_sel:WORD_1 src1_sel:DWORD
	v_and_b32_sdwa v59, v64, v199 dst_sel:DWORD dst_unused:UNUSED_PAD src0_sel:WORD_1 src1_sel:DWORD
	v_add3_u32 v59, v64, v59, s9
	v_add3_u32 v58, v66, v58, s9
	v_and_b32_sdwa v64, v67, v199 dst_sel:DWORD dst_unused:UNUSED_PAD src0_sel:WORD_1 src1_sel:DWORD
	v_and_b32_sdwa v66, v65, v199 dst_sel:DWORD dst_unused:UNUSED_PAD src0_sel:WORD_1 src1_sel:DWORD
	v_add3_u32 v64, v67, v64, s9
	v_add3_u32 v65, v65, v66, s9
	v_and_b32_e32 v64, 0xffff0000, v64
	v_and_b32_e32 v65, 0xffff0000, v65
	v_or_b32_sdwa v71, v64, v58 dst_sel:DWORD dst_unused:UNUSED_PAD src0_sel:DWORD src1_sel:WORD_1
	v_or_b32_sdwa v70, v65, v59 dst_sel:DWORD dst_unused:UNUSED_PAD src0_sel:DWORD src1_sel:WORD_1
	s_waitcnt vmcnt(1)
	v_and_b32_sdwa v64, v95, v199 dst_sel:DWORD dst_unused:UNUSED_PAD src0_sel:WORD_1 src1_sel:DWORD
	v_and_b32_sdwa v65, v93, v199 dst_sel:DWORD dst_unused:UNUSED_PAD src0_sel:WORD_1 src1_sel:DWORD
	v_and_b32_sdwa v58, v94, v199 dst_sel:DWORD dst_unused:UNUSED_PAD src0_sel:WORD_1 src1_sel:DWORD
	v_and_b32_sdwa v59, v92, v199 dst_sel:DWORD dst_unused:UNUSED_PAD src0_sel:WORD_1 src1_sel:DWORD
	v_add3_u32 v64, v95, v64, s9
	v_add3_u32 v65, v93, v65, s9
	s_xor_b32 s16, s16, 0x80
	v_add3_u32 v59, v92, v59, s9
	v_add3_u32 v58, v94, v58, s9
	v_and_b32_e32 v64, 0xffff0000, v64
	v_and_b32_e32 v66, 0xffff0000, v65
	v_add_u32_e32 v57, s16, v32
	v_or_b32_sdwa v65, v64, v58 dst_sel:DWORD dst_unused:UNUSED_PAD src0_sel:DWORD src1_sel:WORD_1
	v_or_b32_sdwa v64, v66, v59 dst_sel:DWORD dst_unused:UNUSED_PAD src0_sel:DWORD src1_sel:WORD_1
	v_and_b32_sdwa v66, v91, v199 dst_sel:DWORD dst_unused:UNUSED_PAD src0_sel:WORD_1 src1_sel:DWORD
	v_and_b32_sdwa v67, v89, v199 dst_sel:DWORD dst_unused:UNUSED_PAD src0_sel:WORD_1 src1_sel:DWORD
	v_lshl_or_b32 v57, v57, 6, v33
	v_and_b32_sdwa v58, v90, v199 dst_sel:DWORD dst_unused:UNUSED_PAD src0_sel:WORD_1 src1_sel:DWORD
	v_and_b32_sdwa v59, v88, v199 dst_sel:DWORD dst_unused:UNUSED_PAD src0_sel:WORD_1 src1_sel:DWORD
	v_add3_u32 v66, v91, v66, s9
	v_add3_u32 v67, v89, v67, s9
	ds_write_b128 v57, v[68:71]
	v_add3_u32 v59, v88, v59, s9
	v_add3_u32 v58, v90, v58, s9
	v_and_b32_e32 v66, 0xffff0000, v66
	v_and_b32_e32 v68, 0xffff0000, v67
	s_addk_i32 s30, 0x80
	s_add_i32 s29, s29, 32
	v_or_b32_sdwa v67, v66, v58 dst_sel:DWORD dst_unused:UNUSED_PAD src0_sel:DWORD src1_sel:WORD_1
	v_or_b32_sdwa v66, v68, v59 dst_sel:DWORD dst_unused:UNUSED_PAD src0_sel:DWORD src1_sel:WORD_1
	s_cmpk_lg_i32 s30, 0x400
	ds_write_b128 v57, v[64:67] offset:4096
	ds_write_b128 v57, v[96:99] offset:16384
	s_waitcnt vmcnt(0)
	ds_write_b128 v57, v[100:103] offset:20480
	s_waitcnt lgkmcnt(0)
	s_barrier
	s_cbranch_scc1 .LBB0_634
	s_lshl_b64 s[30:31], s[22:23], 11
	v_mov_b32_e32 v118, v220
	s_add_u32 s30, s5, s30
	s_addc_u32 s31, s6, s31
	v_ashrrev_i32_e32 v70, 2, v118
	s_lshl_b64 s[34:35], s[0:1], 11
	v_add_u32_e32 v116, 64, v70
	s_add_u32 s34, s7, s34
	v_ashrrev_i32_e32 v117, 31, v116
	s_addc_u32 s35, s8, s35
	v_lshlrev_b64 v[32:33], 11, v[116:117]
	v_min_i32_e32 v34, 0x7f, v70
	v_lshlrev_b32_e32 v35, 4, v118
	v_lshl_add_u64 v[32:33], s[34:35], 0, v[32:33]
	v_and_b32_e32 v176, 48, v35
	v_ashrrev_i32_e32 v35, 31, v34
	v_ashrrev_i32_e32 v71, 31, v70
	v_min_i32_e32 v40, 0x7f, v116
	v_lshl_add_u64 v[130:131], v[32:33], 0, v[176:177]
	v_lshlrev_b64 v[32:33], 11, v[34:35]
	v_lshlrev_b64 v[42:43], 11, v[70:71]
	v_lshl_add_u64 v[32:33], s[30:31], 0, v[32:33]
	v_ashrrev_i32_e32 v41, 31, v40
	v_lshl_add_u64 v[42:43], s[34:35], 0, v[42:43]
	v_lshl_add_u64 v[132:133], v[32:33], 0, v[176:177]
	v_lshlrev_b64 v[32:33], 11, v[40:41]
	v_lshl_add_u64 v[128:129], v[42:43], 0, v[176:177]
	v_lshl_add_u64 v[32:33], s[30:31], 0, v[32:33]
	global_load_dwordx4 v[88:91], v[132:133], off
	global_load_dwordx4 v[92:95], v[128:129], off
	v_lshl_add_u64 v[134:135], v[32:33], 0, v[176:177]
	global_load_dwordx4 v[96:99], v[130:131], off
	global_load_dwordx4 v[108:111], v[134:135], off
	global_load_dwordx4 v[100:103], v[128:129], off offset:64
	global_load_dwordx4 v[104:107], v[132:133], off offset:64
	global_load_dwordx4 v[112:115], v[130:131], off offset:64
	global_load_dwordx4 v[120:123], v[134:135], off offset:64
	v_lshrrev_b32_e32 v71, 4, v118
	v_lshrrev_b32_e32 v117, 2, v118
	v_sub_u32_e32 v126, 0, v71
	v_and_b32_e32 v119, 15, v118
	v_lshrrev_b32_e32 v124, 1, v118
	v_lshlrev_b32_e32 v125, 6, v118
	v_sub_u32_e32 v117, 0, v117
	v_xor_b32_e32 v118, v118, v126
	v_and_or_b32 v119, v124, s25, v119
	v_xor_b32_e32 v71, v71, v117
	v_lshlrev_b32_e32 v117, 4, v118
	v_lshlrev_b32_e32 v145, 6, v119
	v_lshlrev_b32_e32 v71, 4, v71
	v_and_b32_e32 v117, 48, v117
	v_mov_b32_e32 v32, 0
	v_and_b32_e32 v144, 0x13c0, v125
	v_add_u32_e32 v118, 0x2000, v145
	v_and_b32_e32 v146, 48, v71
	v_lshl_or_b32 v147, v70, 6, v117
	s_mov_b32 s23, 0
	s_mov_b32 s1, -2
	v_mov_b32_e32 v33, v32
	v_mov_b32_e32 v34, v32
	v_mov_b32_e32 v35, v32
	v_mov_b32_e32 v40, v32
	v_mov_b32_e32 v41, v32
	v_mov_b32_e32 v42, v32
	v_mov_b32_e32 v43, v32
	v_mov_b32_e32 v48, v32
	v_mov_b32_e32 v49, v32
	v_mov_b32_e32 v50, v32
	v_mov_b32_e32 v51, v32
	v_mov_b32_e32 v56, v32
	v_mov_b32_e32 v57, v32
	v_mov_b32_e32 v58, v32
	v_mov_b32_e32 v59, v32
	v_mov_b32_e32 v64, v32
	v_mov_b32_e32 v65, v32
	v_mov_b32_e32 v66, v32
	v_mov_b32_e32 v67, v32
	v_mov_b32_e32 v68, v32
	v_mov_b32_e32 v69, v32
	v_lshl_or_b32 v156, v116, 6, v117
	v_or_b32_e32 v157, v146, v144
	v_add_u32_e32 v158, v146, v118
	v_mov_b32_e32 v70, v32
	v_mov_b32_e32 v71, v32
	v_mov_b32_e32 v116, v32
	v_mov_b32_e32 v117, v32
	v_mov_b32_e32 v118, v32
	v_mov_b32_e32 v119, v32
	v_mov_b32_e32 v124, v32
	v_mov_b32_e32 v125, v32
	v_mov_b32_e32 v126, v32
	v_mov_b32_e32 v127, v32
	v_mov_b32_e32 v136, v32
	s_waitcnt vmcnt(6)
	ds_write_b128 v147, v[92:95] offset:16384
	ds_write_b128 v147, v[88:91]
	s_waitcnt vmcnt(5)
	ds_write_b128 v156, v[96:99] offset:16384
	s_waitcnt vmcnt(4)
	ds_write_b128 v156, v[108:111]
	v_mov_b32_e32 v88, v32
	v_mov_b32_e32 v89, v32
	v_mov_b32_e32 v90, v32
	v_mov_b32_e32 v91, v32
	v_mov_b32_e32 v92, v32
	v_mov_b32_e32 v93, v32
	v_mov_b32_e32 v94, v32
	v_mov_b32_e32 v95, v32
	v_mov_b32_e32 v96, v32
	v_mov_b32_e32 v97, v32
	v_mov_b32_e32 v98, v32
	v_mov_b32_e32 v99, v32
	v_mov_b32_e32 v108, v32
	v_mov_b32_e32 v109, v32
	v_mov_b32_e32 v110, v32
	v_mov_b32_e32 v111, v32
	v_mov_b32_e32 v137, v32
	v_mov_b32_e32 v138, v32
	v_mov_b32_e32 v139, v32
	v_mov_b32_e32 v140, v32
	v_mov_b32_e32 v141, v32
	v_mov_b32_e32 v142, v32
	v_mov_b32_e32 v143, v32
	v_mov_b32_e32 v148, v32
	v_mov_b32_e32 v149, v32
	v_mov_b32_e32 v150, v32
	v_mov_b32_e32 v151, v32
	v_mov_b32_e32 v152, v32
	v_mov_b32_e32 v153, v32
	v_mov_b32_e32 v154, v32
	v_mov_b32_e32 v155, v32
	s_waitcnt lgkmcnt(0)
.Lrot2_3:
	s_barrier
.LBB0_636:
	s_add_i32 s29, s23, 64
	s_min_u32 s16, s29, 0x3e0
	s_lshl_b32 s16, s16, 1
	v_lshl_add_u64 v[160:161], v[132:133], 0, s[16:17]
	v_lshl_add_u64 v[164:165], v[134:135], 0, s[16:17]
	v_lshl_add_u64 v[168:169], v[128:129], 0, s[16:17]
	v_lshl_add_u64 v[172:173], v[130:131], 0, s[16:17]
	global_load_dwordx4 v[160:163], v[160:161], off
	v_add_u32_e32 v159, v146, v145
	global_load_dwordx4 v[164:167], v[164:165], off
	v_add_u32_e32 v176, v146, v144
	global_load_dwordx4 v[168:171], v[168:169], off
	ds_read_b128 v[178:181], v159
	global_load_dwordx4 v[172:175], v[172:173], off
	ds_read_b128 v[182:185], v159 offset:1024
	ds_read_b128 v[186:189], v176 offset:16384
	ds_read_b128 v[190:193], v176 offset:17408
	ds_read_b128 v[194:197], v159 offset:2048
	ds_read_b128 v[200:203], v159 offset:3072
	ds_read_b128 v[204:207], v176 offset:18432
	ds_read_b128 v[208:211], v176 offset:19456
	s_setprio 1
	s_waitcnt lgkmcnt(5)
	v_mfma_f32_16x16x32_bf16 v[152:155], v[186:189], v[178:181], v[152:155]
	s_waitcnt lgkmcnt(4)
	v_mfma_f32_16x16x32_bf16 v[148:151], v[190:193], v[178:181], v[148:151]
	s_waitcnt lgkmcnt(1)
	v_mfma_f32_16x16x32_bf16 v[140:143], v[204:207], v[178:181], v[140:143]
	s_waitcnt lgkmcnt(0)
	v_mfma_f32_16x16x32_bf16 v[136:139], v[208:211], v[178:181], v[136:139]
	v_mfma_f32_16x16x32_bf16 v[124:127], v[186:189], v[182:185], v[124:127]
	v_mfma_f32_16x16x32_bf16 v[116:119], v[190:193], v[182:185], v[116:119]
	v_mfma_f32_16x16x32_bf16 v[108:111], v[204:207], v[182:185], v[108:111]
	v_mfma_f32_16x16x32_bf16 v[96:99], v[208:211], v[182:185], v[96:99]
	v_mfma_f32_16x16x32_bf16 v[92:95], v[186:189], v[194:197], v[92:95]
	v_mfma_f32_16x16x32_bf16 v[88:91], v[190:193], v[194:197], v[88:91]
	v_mfma_f32_16x16x32_bf16 v[68:71], v[204:207], v[194:197], v[68:71]
	v_mfma_f32_16x16x32_bf16 v[64:67], v[208:211], v[194:197], v[64:67]
	v_mfma_f32_16x16x32_bf16 v[56:59], v[186:189], v[200:203], v[56:59]
	v_mfma_f32_16x16x32_bf16 v[48:51], v[190:193], v[200:203], v[48:51]
	v_mfma_f32_16x16x32_bf16 v[40:43], v[204:207], v[200:203], v[40:43]
	v_mfma_f32_16x16x32_bf16 v[32:35], v[208:211], v[200:203], v[32:35]
	s_setprio 0
	s_min_u32 s16, s23, 0x380
	s_lshl_b32 s16, s16, 1
	s_waitcnt vmcnt(5)
	ds_write_b128 v147, v[100:103] offset:24576
	s_waitcnt vmcnt(4)
	ds_write_b128 v147, v[112:115] offset:28672
	v_lshl_add_u64 v[100:101], v[132:133], 0, s[16:17]
	v_lshl_add_u64 v[102:103], v[134:135], 0, s[16:17]
	v_lshl_add_u64 v[112:113], v[128:129], 0, s[16:17]
	v_lshl_add_u64 v[114:115], v[130:131], 0, s[16:17]
	ds_write_b128 v147, v[104:107] offset:8192
	s_waitcnt vmcnt(4)
	ds_write_b128 v147, v[120:123] offset:12288
	s_waitcnt lgkmcnt(0)
	s_barrier
	global_load_dwordx4 v[104:107], v[100:101], off offset:192
	global_load_dwordx4 v[120:123], v[102:103], off offset:192
	ds_read_b128 v[178:181], v158
	global_load_dwordx4 v[100:103], v[112:113], off offset:192
	ds_read_b128 v[182:185], v157 offset:24576
	global_load_dwordx4 v[112:115], v[114:115], off offset:192
	ds_read_b128 v[186:189], v158 offset:1024
	ds_read_b128 v[190:193], v157 offset:25600
	ds_read_b128 v[194:197], v158 offset:2048
	ds_read_b128 v[200:203], v157 offset:26624
	ds_read_b128 v[204:207], v158 offset:3072
	ds_read_b128 v[208:211], v157 offset:27648
	s_setprio 1
	s_waitcnt lgkmcnt(6)
	v_mfma_f32_16x16x32_bf16 v[152:155], v[182:185], v[178:181], v[152:155]
	s_waitcnt lgkmcnt(4)
	v_mfma_f32_16x16x32_bf16 v[148:151], v[190:193], v[178:181], v[148:151]
	s_waitcnt lgkmcnt(2)
	v_mfma_f32_16x16x32_bf16 v[140:143], v[200:203], v[178:181], v[140:143]
	s_waitcnt lgkmcnt(0)
	v_mfma_f32_16x16x32_bf16 v[136:139], v[208:211], v[178:181], v[136:139]
	v_mfma_f32_16x16x32_bf16 v[124:127], v[182:185], v[186:189], v[124:127]
	v_mfma_f32_16x16x32_bf16 v[116:119], v[190:193], v[186:189], v[116:119]
	v_mfma_f32_16x16x32_bf16 v[108:111], v[200:203], v[186:189], v[108:111]
	v_mfma_f32_16x16x32_bf16 v[96:99], v[208:211], v[186:189], v[96:99]
	v_mfma_f32_16x16x32_bf16 v[92:95], v[182:185], v[194:197], v[92:95]
	v_mfma_f32_16x16x32_bf16 v[88:91], v[190:193], v[194:197], v[88:91]
	v_mfma_f32_16x16x32_bf16 v[68:71], v[200:203], v[194:197], v[68:71]
	v_mfma_f32_16x16x32_bf16 v[64:67], v[208:211], v[194:197], v[64:67]
	v_mfma_f32_16x16x32_bf16 v[56:59], v[182:185], v[204:207], v[56:59]
	v_mfma_f32_16x16x32_bf16 v[48:51], v[190:193], v[204:207], v[48:51]
	v_mfma_f32_16x16x32_bf16 v[40:43], v[200:203], v[204:207], v[40:43]
	v_mfma_f32_16x16x32_bf16 v[32:35], v[208:211], v[204:207], v[32:35]
	s_setprio 0
	s_add_i32 s1, s1, 2
	s_cmp_lt_u32 s1, 30
	s_mov_b32 s23, s29
	s_waitcnt vmcnt(7)
	ds_write_b128 v147, v[160:163]
	s_waitcnt vmcnt(6)
	ds_write_b128 v156, v[164:167]
	s_waitcnt vmcnt(5)
	ds_write_b128 v147, v[168:171] offset:16384
	s_waitcnt vmcnt(4)
	ds_write_b128 v156, v[172:175] offset:16384
	s_waitcnt lgkmcnt(0)
	s_cbranch_scc1 .Lrot2_3
	s_barrier
	s_waitcnt vmcnt(1)
	v_mov_b32_e32 v102, v220
	s_nop 0
	v_ashrrev_i32_e32 v100, 1, v102
	v_and_b32_e32 v100, 0xffffffc0, v100
	v_add_u32_e32 v100, s22, v100
	v_and_or_b32 v192, v102, 15, v100
	v_ashrrev_i32_e32 v193, 31, v192
	v_lshl_add_u64 v[100:101], v[192:193], 2, s[10:11]
	global_load_dword v224, v[100:101], off
	v_bfe_u32 v100, v102, 4, 2
	v_and_b32_e32 v101, 64, v102
	v_lshlrev_b32_e32 v102, 2, v100
	v_or3_b32 v182, v102, v101, s0
	v_ashrrev_i32_e32 v183, 31, v182
	v_cmp_eq_u32_e32 vcc, 0, v100
	v_lshlrev_b64 v[100:101], 2, v[182:183]
	v_lshl_add_u64 v[102:103], s[70:71], 0, v[100:101]
	v_lshlrev_b64 v[104:105], 12, v[192:193]
	v_lshl_add_u64 v[106:107], v[102:103], 0, v[104:105]
	global_load_dwordx4 v[206:209], v[106:107], off offset:64
	global_load_dwordx4 v[202:205], v[106:107], off
	v_or_b32_e32 v188, 16, v192
	v_or_b32_e32 v184, 32, v192
	v_or_b32_e32 v178, 48, v192
	v_lshl_add_u64 v[104:105], s[70:71], 0, v[104:105]
	v_ashrrev_i32_e32 v189, 31, v188
	v_ashrrev_i32_e32 v185, 31, v184
	v_ashrrev_i32_e32 v179, 31, v178
	v_lshl_add_u64 v[196:197], v[104:105], 0, v[100:101]
	v_lshlrev_b64 v[218:219], 11, v[192:193]
	s_waitcnt vmcnt(3)
	v_lshl_add_u64 v[112:113], v[188:189], 2, s[10:11]
	v_lshlrev_b64 v[194:195], 12, v[188:189]
	v_lshl_add_u64 v[114:115], v[184:185], 2, s[10:11]
	v_lshlrev_b64 v[190:191], 12, v[184:185]
	v_lshlrev_b64 v[186:187], 12, v[178:179]
	v_lshlrev_b64 v[180:181], 1, v[182:183]
	v_lshl_add_u64 v[120:121], v[178:179], 2, s[10:11]
	v_lshl_add_u64 v[122:123], s[12:13], 0, v[218:219]
	global_load_dword v201, v[112:113], off
	v_lshl_add_u64 v[112:113], v[102:103], 0, v[194:195]
	global_load_dword v200, v[114:115], off
	v_lshl_add_u64 v[114:115], v[102:103], 0, v[190:191]
	v_lshl_add_u64 v[102:103], v[102:103], 0, v[186:187]
	global_load_dword v176, v[120:121], off
	v_lshl_add_u64 v[222:223], v[122:123], 0, v[180:181]
	global_load_dwordx4 v[210:213], v[106:107], off offset:128
	global_load_dwordx4 v[214:217], v[106:107], off offset:192
	global_load_dwordx4 v[172:175], v[112:113], off
	global_load_dwordx4 v[168:171], v[112:113], off offset:64
	global_load_dwordx4 v[164:167], v[112:113], off offset:128
	global_load_dwordx4 v[160:163], v[112:113], off offset:192
	global_load_dwordx4 v[156:159], v[114:115], off
	global_load_dwordx4 v[144:147], v[114:115], off offset:64
	global_load_dwordx4 v[132:135], v[114:115], off offset:128
	global_load_dwordx4 v[128:131], v[114:115], off offset:192
	s_waitcnt vmcnt(15)
	v_fmamk_f32 v100, v224, 0x3a800000, v198
	v_mul_f32_e32 v101, 0x4b800000, v100
	v_cmp_gt_f32_e64 s[0:1], s26, v100
	s_nop 1
	v_cndmask_b32_e64 v100, v100, v101, s[0:1]
	v_rsq_f32_e32 v224, v100
	global_load_dwordx4 v[120:123], v[102:103], off
	global_load_dwordx4 v[112:115], v[102:103], off offset:64
	global_load_dwordx4 v[104:107], v[102:103], off offset:128
	s_nop 0
	global_load_dwordx4 v[100:103], v[102:103], off offset:192
	v_mul_f32_e32 v225, 0x45800000, v224
	v_cndmask_b32_e64 v224, v224, v225, s[0:1]
	v_mul_f32_e32 v154, v154, v224
	v_mul_f32_e32 v155, v155, v224
	v_mul_f32_e32 v150, v150, v224
	v_mul_f32_e32 v151, v151, v224
	v_mul_f32_e32 v154, 0xbfb8aa3b, v154
	v_mul_f32_e32 v155, 0xbfb8aa3b, v155
	v_mul_f32_e32 v150, 0xbfb8aa3b, v150
	v_mul_f32_e32 v151, 0xbfb8aa3b, v151
	v_exp_f32_e32 v154, v154
	v_exp_f32_e32 v155, v155
	v_exp_f32_e32 v150, v150
	v_exp_f32_e32 v151, v151
	v_mul_f32_e32 v152, v152, v224
	v_mul_f32_e32 v153, v153, v224
	v_mul_f32_e32 v148, v148, v224
	v_mul_f32_e32 v149, v149, v224
	v_mul_f32_e32 v152, 0xbfb8aa3b, v152
	v_mul_f32_e32 v153, 0xbfb8aa3b, v153
	v_mul_f32_e32 v148, 0xbfb8aa3b, v148
	v_mul_f32_e32 v149, 0xbfb8aa3b, v149
	v_add_f32_e32 v154, 1.0, v154
	v_add_f32_e32 v155, 1.0, v155
	v_add_f32_e32 v227, 1.0, v150
	v_add_f32_e32 v228, 1.0, v151
	v_exp_f32_e32 v152, v152
	v_exp_f32_e32 v153, v153
	v_exp_f32_e32 v148, v148
	v_exp_f32_e32 v149, v149
	v_rcp_f32_e32 v150, v154
	v_rcp_f32_e32 v151, v155
	v_rcp_f32_e32 v154, v227
	v_rcp_f32_e32 v155, v228
	v_mul_f32_e32 v140, v140, v224
	v_mul_f32_e32 v140, 0xbfb8aa3b, v140
	v_add_f32_e32 v152, 1.0, v152
	v_add_f32_e32 v153, 1.0, v153
	v_add_f32_e32 v225, 1.0, v148
	v_add_f32_e32 v226, 1.0, v149
	s_waitcnt vmcnt(18)
	v_pk_fma_f32 v[82:83], v[82:83], v[154:155], v[208:209]
	v_exp_f32_e32 v154, v140
	v_mul_f32_e32 v140, v141, v224
	v_rcp_f32_e32 v148, v152
	v_rcp_f32_e32 v149, v153
	v_rcp_f32_e32 v152, v225
	v_rcp_f32_e32 v153, v226
	v_mul_f32_e32 v140, 0xbfb8aa3b, v140
	v_mul_f32_e32 v142, v142, v224
	v_exp_f32_e32 v141, v140
	v_mul_f32_e32 v142, 0xbfb8aa3b, v142
	v_mul_f32_e32 v143, v143, v224
	v_exp_f32_e32 v142, v142
	v_mul_f32_e32 v143, 0xbfb8aa3b, v143
	v_exp_f32_e32 v143, v143
	s_waitcnt vmcnt(17)
	v_pk_fma_f32 v[84:85], v[84:85], v[148:149], v[202:203]
	v_pk_fma_f32 v[80:81], v[80:81], v[152:153], v[206:207]
	v_mul_f32_e32 v148, v85, v85
	v_mul_f32_e32 v152, v81, v81
	v_add_f32_e32 v141, 1.0, v141
	v_pk_fma_f32 v[86:87], v[86:87], v[150:151], v[204:205]
	v_pk_fma_f32 v[148:149], v[84:85], v[84:85], v[148:149] op_sel_hi:[1,1,0]
	v_pk_fma_f32 v[152:153], v[80:81], v[80:81], v[152:153] op_sel_hi:[1,1,0]
	v_rcp_f32_e32 v155, v141
	v_add_f32_e32 v141, 1.0, v142
	v_mul_f32_e32 v150, v87, v87
	v_pk_fma_f32 v[148:149], v[86:87], v[86:87], v[148:149]
	v_pk_fma_f32 v[152:153], v[82:83], v[82:83], v[152:153]
	v_mul_f32_e32 v140, v83, v83
	v_rcp_f32_e32 v142, v141
	v_add_f32_e32 v141, 1.0, v143
	v_mul_f32_e32 v136, v136, v224
	v_pk_add_f32 v[148:149], v[150:151], v[148:149] op_sel_hi:[0,1]
	v_rcp_f32_e32 v143, v141
	v_pk_add_f32 v[140:141], v[140:141], v[152:153] op_sel_hi:[0,1]
	v_mul_f32_e32 v136, 0xbfb8aa3b, v136
	v_pk_add_f32 v[140:141], v[148:149], v[140:141]
	v_exp_f32_e32 v148, v136
	v_mul_f32_e32 v136, v137, v224
	v_mul_f32_e32 v136, 0xbfb8aa3b, v136
	v_mul_f32_e32 v138, v138, v224
	v_exp_f32_e32 v137, v136
	v_mul_f32_e32 v138, 0xbfb8aa3b, v138
	v_mul_f32_e32 v139, v139, v224
	v_add_f32_e32 v154, 1.0, v154
	v_exp_f32_e32 v138, v138
	v_mul_f32_e32 v139, 0xbfb8aa3b, v139
	v_rcp_f32_e32 v154, v154
	v_exp_f32_e32 v139, v139
	v_add_f32_e32 v137, 1.0, v137
	v_add_f32_e32 v148, 1.0, v148
	v_rcp_f32_e32 v149, v137
	v_add_f32_e32 v137, 1.0, v138
	s_waitcnt vmcnt(13)
	v_pk_fma_f32 v[76:77], v[76:77], v[154:155], v[210:211]
	v_rcp_f32_e32 v148, v148
	v_rcp_f32_e32 v138, v137
	v_add_f32_e32 v137, 1.0, v139
	v_pk_fma_f32 v[78:79], v[78:79], v[142:143], v[212:213]
	v_mul_f32_e32 v142, v77, v77
	v_rcp_f32_e32 v139, v137
	v_pk_fma_f32 v[142:143], v[76:77], v[76:77], v[142:143] op_sel_hi:[1,1,0]
	v_mul_f32_e32 v136, v79, v79
	v_pk_fma_f32 v[142:143], v[78:79], v[78:79], v[142:143]
	v_lshl_add_u64 v[150:151], s[72:73], 0, v[218:219]
	v_pk_add_f32 v[136:137], v[136:137], v[142:143] op_sel_hi:[0,1]
	s_waitcnt vmcnt(12)
	v_pk_fma_f32 v[72:73], v[72:73], v[148:149], v[214:215]
	v_lshl_add_u64 v[150:151], v[150:151], 0, v[180:181]
	v_pk_add_f32 v[136:137], v[136:137], v[140:141]
	v_pk_fma_f32 v[74:75], v[74:75], v[138:139], v[216:217]
	v_and_b32_sdwa v138, v86, v199 dst_sel:DWORD dst_unused:UNUSED_PAD src0_sel:WORD_1 src1_sel:DWORD
	v_and_b32_sdwa v139, v84, v199 dst_sel:DWORD dst_unused:UNUSED_PAD src0_sel:WORD_1 src1_sel:DWORD
	global_store_dwordx4 v[196:197], v[84:87], off
	s_nop 1
	v_add3_u32 v84, v84, v139, s9
	v_add3_u32 v86, v86, v138, s9
	v_and_b32_sdwa v138, v87, v199 dst_sel:DWORD dst_unused:UNUSED_PAD src0_sel:WORD_1 src1_sel:DWORD
	v_and_b32_sdwa v139, v85, v199 dst_sel:DWORD dst_unused:UNUSED_PAD src0_sel:WORD_1 src1_sel:DWORD
	v_add3_u32 v87, v87, v138, s9
	v_add3_u32 v85, v85, v139, s9
	v_and_b32_e32 v87, 0xffff0000, v87
	v_and_b32_e32 v138, 0xffff0000, v85
	v_or_b32_sdwa v85, v87, v86 dst_sel:DWORD dst_unused:UNUSED_PAD src0_sel:DWORD src1_sel:WORD_1
	v_or_b32_sdwa v84, v138, v84 dst_sel:DWORD dst_unused:UNUSED_PAD src0_sel:DWORD src1_sel:WORD_1
	global_store_dwordx2 v[222:223], v[84:85], off
	global_store_dwordx4 v[196:197], v[80:83], off offset:64
	v_and_b32_sdwa v84, v82, v199 dst_sel:DWORD dst_unused:UNUSED_PAD src0_sel:WORD_1 src1_sel:DWORD
	v_and_b32_sdwa v85, v80, v199 dst_sel:DWORD dst_unused:UNUSED_PAD src0_sel:WORD_1 src1_sel:DWORD
	v_add3_u32 v82, v82, v84, s9
	v_and_b32_sdwa v84, v83, v199 dst_sel:DWORD dst_unused:UNUSED_PAD src0_sel:WORD_1 src1_sel:DWORD
	v_add3_u32 v80, v80, v85, s9
	v_and_b32_sdwa v85, v81, v199 dst_sel:DWORD dst_unused:UNUSED_PAD src0_sel:WORD_1 src1_sel:DWORD
	v_add3_u32 v83, v83, v84, s9
	v_add3_u32 v81, v81, v85, s9
	v_and_b32_e32 v83, 0xffff0000, v83
	v_and_b32_e32 v84, 0xffff0000, v81
	v_or_b32_sdwa v81, v83, v82 dst_sel:DWORD dst_unused:UNUSED_PAD src0_sel:DWORD src1_sel:WORD_1
	v_add_co_u32_e64 v82, s[0:1], s27, v150
	v_or_b32_sdwa v80, v84, v80 dst_sel:DWORD dst_unused:UNUSED_PAD src0_sel:DWORD src1_sel:WORD_1
	s_nop 0
	v_addc_co_u32_e64 v83, s[0:1], 0, v151, s[0:1]
	global_store_dwordx2 v[82:83], v[80:81], off offset:32
	global_store_dwordx4 v[196:197], v[76:79], off offset:128
	v_and_b32_sdwa v80, v78, v199 dst_sel:DWORD dst_unused:UNUSED_PAD src0_sel:WORD_1 src1_sel:DWORD
	v_and_b32_sdwa v81, v76, v199 dst_sel:DWORD dst_unused:UNUSED_PAD src0_sel:WORD_1 src1_sel:DWORD
	v_add3_u32 v76, v76, v81, s9
	v_add3_u32 v78, v78, v80, s9
	v_and_b32_sdwa v80, v79, v199 dst_sel:DWORD dst_unused:UNUSED_PAD src0_sel:WORD_1 src1_sel:DWORD
	v_and_b32_sdwa v81, v77, v199 dst_sel:DWORD dst_unused:UNUSED_PAD src0_sel:WORD_1 src1_sel:DWORD
	v_add3_u32 v79, v79, v80, s9
	v_add3_u32 v77, v77, v81, s9
	v_and_b32_e32 v79, 0xffff0000, v79
	v_and_b32_e32 v80, 0xffff0000, v77
	v_or_b32_sdwa v77, v79, v78 dst_sel:DWORD dst_unused:UNUSED_PAD src0_sel:DWORD src1_sel:WORD_1
	v_or_b32_sdwa v76, v80, v76 dst_sel:DWORD dst_unused:UNUSED_PAD src0_sel:DWORD src1_sel:WORD_1
	global_store_dwordx2 v[82:83], v[76:77], off offset:64
	global_store_dwordx4 v[196:197], v[72:75], off offset:192
	v_and_b32_sdwa v77, v72, v199 dst_sel:DWORD dst_unused:UNUSED_PAD src0_sel:WORD_1 src1_sel:DWORD
	v_add3_u32 v78, v72, v77, s9
	v_and_b32_sdwa v77, v75, v199 dst_sel:DWORD dst_unused:UNUSED_PAD src0_sel:WORD_1 src1_sel:DWORD
	v_and_b32_sdwa v79, v73, v199 dst_sel:DWORD dst_unused:UNUSED_PAD src0_sel:WORD_1 src1_sel:DWORD
	v_and_b32_sdwa v76, v74, v199 dst_sel:DWORD dst_unused:UNUSED_PAD src0_sel:WORD_1 src1_sel:DWORD
	v_add3_u32 v77, v75, v77, s9
	v_add3_u32 v79, v73, v79, s9
	v_add3_u32 v76, v74, v76, s9
	v_and_b32_e32 v77, 0xffff0000, v77
	v_and_b32_e32 v79, 0xffff0000, v79
	v_or_b32_sdwa v77, v77, v76 dst_sel:DWORD dst_unused:UNUSED_PAD src0_sel:DWORD src1_sel:WORD_1
	v_or_b32_sdwa v76, v79, v78 dst_sel:DWORD dst_unused:UNUSED_PAD src0_sel:DWORD src1_sel:WORD_1
	global_store_dwordx2 v[82:83], v[76:77], off offset:96
	v_mul_f32_e32 v76, v73, v73
	v_pk_fma_f32 v[72:73], v[72:73], v[72:73], v[76:77] op_sel_hi:[1,1,0]
	s_nop 0
	v_pk_fma_f32 v[72:73], v[74:75], v[74:75], v[72:73]
	v_mul_f32_e32 v74, v75, v75
	v_pk_add_f32 v[72:73], v[74:75], v[72:73] op_sel_hi:[0,1]
	v_pk_add_f32 v[72:73], v[72:73], v[136:137]
	s_nop 0
	v_mov_b32_e32 v73, v72
	s_nop 1
	v_permlane32_swap_b32_e32 v72, v73
	v_add_f32_e32 v72, v72, v73
	v_mov_b32_e32 v73, v72
	s_nop 1
	v_permlane16_swap_b32_e32 v72, v73
	s_and_saveexec_b64 s[0:1], vcc
	s_cbranch_execz .LBB0_639
	v_lshl_add_u64 v[74:75], v[192:193], 2, s[14:15]
	v_add_f32_e32 v72, v72, v73
	global_atomic_add_f32 v[74:75], v72, off

.LBB0_968:
	s_ashr_i32 s12, s38, 7
	s_lshl_b32 s1, s38, 6
	s_and_b32 s14, s1, 0x380
	s_lshl_b32 s1, s38, 7
	s_ashr_i32 s13, s12, 31
	s_ashr_i32 s0, s38, 4
	s_and_b32 s1, s1, 0x80
	s_lshl_b64 s[16:17], s[12:13], 25
	s_add_u32 s10, s4, s16
	s_addc_u32 s13, s5, s17
	s_lshl_b32 s15, s0, 22
	s_and_b32 s15, s15, 0x1c00000
	s_add_u32 s10, s10, s15
	s_addc_u32 s13, s13, 0
	s_lshl_b32 s15, s14, 12
	s_add_u32 s16, s10, s15
	s_addc_u32 s17, s13, 0
	s_cmpk_lt_u32 s38, 0x80
	s_cselect_b32 s10, s20, 0x1800000
	s_add_u32 s10, s72, s10
	v_mov_b32_e32 v13, v220
	s_addc_u32 s13, s73, 0
	s_lshl_b32 s15, s1, 13
	s_add_u32 s40, s10, s15
	v_ashrrev_i32_e32 v30, 2, v13
	v_add_u32_e32 v32, 64, v30
	s_addc_u32 s41, s13, 0
	s_xor_b32 s10, s14, 0x3fe
	v_ashrrev_i32_e32 v33, 31, v32
	v_lshlrev_b64 v[0:1], 13, v[32:33]
	v_min_i32_e32 v2, s10, v30
	v_lshlrev_b32_e32 v3, 4, v13
	v_lshl_add_u64 v[0:1], s[40:41], 0, v[0:1]
	v_and_b32_e32 v80, 48, v3
	v_ashrrev_i32_e32 v3, 31, v2
	v_min_i32_e32 v4, s10, v32
	v_lshl_add_u64 v[84:85], v[0:1], 0, v[80:81]
	v_lshlrev_b64 v[0:1], 12, v[2:3]
	v_ashrrev_i32_e32 v31, 31, v30
	v_lshl_add_u64 v[0:1], s[16:17], 0, v[0:1]
	v_ashrrev_i32_e32 v5, 31, v4
	v_lshlrev_b64 v[6:7], 13, v[30:31]
	v_lshl_add_u64 v[86:87], v[0:1], 0, v[80:81]
	v_lshlrev_b64 v[0:1], 12, v[4:5]
	v_lshl_add_u64 v[6:7], s[40:41], 0, v[6:7]
	v_lshl_add_u64 v[0:1], s[16:17], 0, v[0:1]
	v_lshl_add_u64 v[82:83], v[6:7], 0, v[80:81]
	v_lshl_add_u64 v[88:89], v[0:1], 0, v[80:81]
	global_load_dwordx4 v[14:17], v[86:87], off
	global_load_dwordx4 v[18:21], v[82:83], off
	global_load_dwordx4 v[22:25], v[84:85], off
	global_load_dwordx4 v[26:29], v[88:89], off
	global_load_dwordx4 v[64:67], v[82:83], off offset:64
	global_load_dwordx4 v[68:71], v[84:85], off offset:64
	global_load_dwordx4 v[72:75], v[86:87], off offset:64
	global_load_dwordx4 v[76:79], v[88:89], off offset:64
	v_lshrrev_b32_e32 v31, 4, v13
	v_lshrrev_b32_e32 v33, 2, v13
	v_sub_u32_e32 v37, 0, v31
	v_and_b32_e32 v34, 15, v13
	v_lshrrev_b32_e32 v35, 1, v13
	v_lshlrev_b32_e32 v36, 6, v13
	v_sub_u32_e32 v33, 0, v33
	v_xor_b32_e32 v13, v13, v37
	v_and_or_b32 v34, v35, s22, v34
	v_xor_b32_e32 v31, v31, v33
	v_lshlrev_b32_e32 v13, 4, v13
	v_lshlrev_b32_e32 v33, 6, v34
	v_lshlrev_b32_e32 v31, 4, v31
	v_and_b32_e32 v13, 48, v13
	v_and_b32_e32 v35, 0x13c0, v36
	v_add_u32_e32 v34, 0x2000, v33
	v_and_b32_e32 v31, 48, v31
	v_lshl_or_b32 v80, v30, 6, v13
	s_mov_b32 s13, -2
	s_mov_b32 s15, s11
	v_mov_b32_e32 v0, 0
	v_mov_b32_e32 v1, v81
	v_mov_b32_e32 v2, v81
	v_mov_b32_e32 v3, v81
	v_mov_b32_e32 v4, 0
	v_mov_b32_e32 v5, v81
	v_mov_b32_e32 v6, v81
	v_mov_b32_e32 v7, v81
	v_mov_b32_e32 v8, 0
	v_mov_b32_e32 v9, v81
	v_mov_b32_e32 v10, v81
	v_mov_b32_e32 v11, v81
	v_mov_b32_e32 v12, 0
	v_lshl_or_b32 v92, v32, 6, v13
	v_or_b32_e32 v93, v31, v35
	v_add_u32_e32 v94, v31, v33
	v_add_u32_e32 v95, v31, v35
	v_add_u32_e32 v96, v31, v34
	v_mov_b32_e32 v13, v81
	v_mov_b32_e32 v30, v81
	v_mov_b32_e32 v31, v81
	v_mov_b32_e32 v32, 0
	v_mov_b32_e32 v33, v81
	v_mov_b32_e32 v34, v81
	v_mov_b32_e32 v35, v81
	v_mov_b32_e32 v36, 0
	v_mov_b32_e32 v37, v81
	v_mov_b32_e32 v38, v81
	s_waitcnt vmcnt(6)
	ds_write_b128 v80, v[18:21] offset:16384
	s_waitcnt vmcnt(5)
	ds_write_b128 v92, v[22:25] offset:16384
	ds_write_b128 v80, v[14:17]
	s_waitcnt vmcnt(4)
	ds_write_b128 v92, v[26:29]
	v_mov_b32_e32 v14, v81
	v_mov_b32_e32 v15, v81
	v_mov_b32_e32 v16, 0
	v_mov_b32_e32 v17, v81
	v_mov_b32_e32 v18, v81
	v_mov_b32_e32 v19, v81
	v_mov_b32_e32 v20, 0
	v_mov_b32_e32 v21, v81
	v_mov_b32_e32 v22, v81
	v_mov_b32_e32 v23, v81
	v_mov_b32_e32 v24, 0
	v_mov_b32_e32 v25, v81
	v_mov_b32_e32 v26, v81
	v_mov_b32_e32 v27, v81
	v_mov_b32_e32 v28, 0
	v_mov_b32_e32 v29, v81
	v_mov_b32_e32 v39, v81
	v_mov_b32_e32 v40, 0
	v_mov_b32_e32 v41, v81
	v_mov_b32_e32 v42, v81
	v_mov_b32_e32 v43, v81
	v_mov_b32_e32 v44, 0
	v_mov_b32_e32 v45, v81
	v_mov_b32_e32 v46, v81
	v_mov_b32_e32 v47, v81
	v_mov_b32_e32 v48, 0
	v_mov_b32_e32 v49, v81
	v_mov_b32_e32 v50, v81
	v_mov_b32_e32 v51, v81
	v_mov_b32_e32 v52, 0
	v_mov_b32_e32 v53, v81
	v_mov_b32_e32 v54, v81
	v_mov_b32_e32 v55, v81
	v_mov_b32_e32 v56, 0
	v_mov_b32_e32 v57, v81
	v_mov_b32_e32 v58, v81
	v_mov_b32_e32 v59, v81
	v_mov_b32_e32 v60, 0
	v_mov_b32_e32 v61, v81
	v_mov_b32_e32 v62, v81
	v_mov_b32_e32 v63, v81
	s_waitcnt lgkmcnt(0)
.Lrot2_2:
	s_barrier
.LBB0_969:
	s_add_i32 s16, s15, 64
	s_min_u32 s10, s16, 0xfe0
	s_lshl_b32 s10, s10, 1
	v_lshl_add_u64 v[98:99], v[86:87], 0, s[10:11]
	v_lshl_add_u64 v[102:103], v[88:89], 0, s[10:11]
	v_lshl_add_u64 v[106:107], v[82:83], 0, s[10:11]
	v_lshl_add_u64 v[110:111], v[84:85], 0, s[10:11]
	global_load_dwordx4 v[98:101], v[98:99], off
	ds_read_b128 v[114:117], v94
	global_load_dwordx4 v[102:105], v[102:103], off
	ds_read_b128 v[118:121], v94 offset:1024
	global_load_dwordx4 v[106:109], v[106:107], off
	ds_read_b128 v[122:125], v95 offset:16384
	global_load_dwordx4 v[110:113], v[110:111], off
	ds_read_b128 v[126:129], v95 offset:17408
	ds_read_b128 v[130:133], v94 offset:2048
	ds_read_b128 v[134:137], v94 offset:3072
	ds_read_b128 v[138:141], v95 offset:18432
	ds_read_b128 v[142:145], v95 offset:19456
	s_setprio 1
	s_waitcnt lgkmcnt(5)
	v_mfma_f32_16x16x32_bf16 v[60:63], v[114:117], v[122:125], v[60:63]
	s_waitcnt lgkmcnt(4)
	v_mfma_f32_16x16x32_bf16 v[56:59], v[114:117], v[126:129], v[56:59]
	s_waitcnt lgkmcnt(1)
	v_mfma_f32_16x16x32_bf16 v[52:55], v[114:117], v[138:141], v[52:55]
	s_waitcnt lgkmcnt(0)
	v_mfma_f32_16x16x32_bf16 v[48:51], v[114:117], v[142:145], v[48:51]
	v_mfma_f32_16x16x32_bf16 v[44:47], v[118:121], v[122:125], v[44:47]
	v_mfma_f32_16x16x32_bf16 v[40:43], v[118:121], v[126:129], v[40:43]
	v_mfma_f32_16x16x32_bf16 v[36:39], v[118:121], v[138:141], v[36:39]
	v_mfma_f32_16x16x32_bf16 v[32:35], v[118:121], v[142:145], v[32:35]
	v_mfma_f32_16x16x32_bf16 v[28:31], v[130:133], v[122:125], v[28:31]
	v_mfma_f32_16x16x32_bf16 v[24:27], v[130:133], v[126:129], v[24:27]
	v_mfma_f32_16x16x32_bf16 v[20:23], v[130:133], v[138:141], v[20:23]
	v_mfma_f32_16x16x32_bf16 v[16:19], v[130:133], v[142:145], v[16:19]
	v_mfma_f32_16x16x32_bf16 v[12:15], v[134:137], v[122:125], v[12:15]
	v_mfma_f32_16x16x32_bf16 v[8:11], v[134:137], v[126:129], v[8:11]
	v_mfma_f32_16x16x32_bf16 v[4:7], v[134:137], v[138:141], v[4:7]
	v_mfma_f32_16x16x32_bf16 v[0:3], v[134:137], v[142:145], v[0:3]
	s_setprio 0
	s_min_u32 s10, s15, 0xf80
	s_lshl_b32 s10, s10, 1
	s_waitcnt vmcnt(5)
	ds_write_b128 v80, v[64:67] offset:24576
	s_waitcnt vmcnt(4)
	ds_write_b128 v80, v[68:71] offset:28672
	v_lshl_add_u64 v[64:65], v[86:87], 0, s[10:11]
	v_lshl_add_u64 v[66:67], v[88:89], 0, s[10:11]
	v_lshl_add_u64 v[68:69], v[82:83], 0, s[10:11]
	v_lshl_add_u64 v[70:71], v[84:85], 0, s[10:11]
	s_waitcnt vmcnt(5)
	ds_write_b128 v80, v[72:75] offset:8192
	s_waitcnt vmcnt(4)
	ds_write_b128 v80, v[76:79] offset:12288
	s_waitcnt lgkmcnt(0)
	s_barrier
	global_load_dwordx4 v[72:75], v[64:65], off offset:192
	global_load_dwordx4 v[76:79], v[66:67], off offset:192
	ds_read_b128 v[114:117], v96
	global_load_dwordx4 v[64:67], v[68:69], off offset:192
	ds_read_b128 v[118:121], v93 offset:24576
	global_load_dwordx4 v[68:71], v[70:71], off offset:192
	ds_read_b128 v[122:125], v96 offset:1024
	ds_read_b128 v[126:129], v93 offset:25600
	ds_read_b128 v[130:133], v96 offset:2048
	ds_read_b128 v[134:137], v93 offset:26624
	ds_read_b128 v[138:141], v96 offset:3072
	ds_read_b128 v[142:145], v93 offset:27648
	s_setprio 1
	s_waitcnt lgkmcnt(6)
	v_mfma_f32_16x16x32_bf16 v[60:63], v[114:117], v[118:121], v[60:63]
	s_waitcnt lgkmcnt(4)
	v_mfma_f32_16x16x32_bf16 v[56:59], v[114:117], v[126:129], v[56:59]
	s_waitcnt lgkmcnt(2)
	v_mfma_f32_16x16x32_bf16 v[52:55], v[114:117], v[134:137], v[52:55]
	s_waitcnt lgkmcnt(0)
	v_mfma_f32_16x16x32_bf16 v[48:51], v[114:117], v[142:145], v[48:51]
	v_mfma_f32_16x16x32_bf16 v[44:47], v[122:125], v[118:121], v[44:47]
	v_mfma_f32_16x16x32_bf16 v[40:43], v[122:125], v[126:129], v[40:43]
	v_mfma_f32_16x16x32_bf16 v[36:39], v[122:125], v[134:137], v[36:39]
	v_mfma_f32_16x16x32_bf16 v[32:35], v[122:125], v[142:145], v[32:35]
	v_mfma_f32_16x16x32_bf16 v[28:31], v[130:133], v[118:121], v[28:31]
	v_mfma_f32_16x16x32_bf16 v[24:27], v[130:133], v[126:129], v[24:27]
	v_mfma_f32_16x16x32_bf16 v[20:23], v[130:133], v[134:137], v[20:23]
	v_mfma_f32_16x16x32_bf16 v[16:19], v[130:133], v[142:145], v[16:19]
	v_mfma_f32_16x16x32_bf16 v[12:15], v[138:141], v[118:121], v[12:15]
	v_mfma_f32_16x16x32_bf16 v[8:11], v[138:141], v[126:129], v[8:11]
	v_mfma_f32_16x16x32_bf16 v[4:7], v[138:141], v[134:137], v[4:7]
	v_mfma_f32_16x16x32_bf16 v[0:3], v[138:141], v[142:145], v[0:3]
	s_setprio 0
	s_add_i32 s13, s13, 2
	s_cmpk_lt_u32 s13, 0x7e
	s_mov_b32 s15, s16
	s_waitcnt vmcnt(7)
	ds_write_b128 v80, v[98:101]
	s_waitcnt vmcnt(6)
	ds_write_b128 v92, v[102:105]
	s_waitcnt vmcnt(5)
	ds_write_b128 v80, v[106:109] offset:16384
	s_waitcnt vmcnt(4)
	ds_write_b128 v92, v[110:113] offset:16384
	s_waitcnt lgkmcnt(0)
	s_cbranch_scc1 .Lrot2_2
	s_barrier
	s_lshl_b32 s12, s12, 13
	v_mov_b32_e32 v200, v220
	s_ashr_i32 s13, s12, 31
	s_lshl_b64 s[12:13], s[12:13], 2
	s_waitcnt vmcnt(1)
	v_and_b32_e32 v64, 0x4f, v200
	v_or_b32_e32 v201, s1, v64
	s_add_u32 s12, s6, s12
	s_addc_u32 s13, s7, s13
	v_lshlrev_b32_e32 v80, 2, v201
	v_lshl_add_u64 v[64:65], s[12:13], 0, v[80:81]
	v_add_co_u32_e32 v66, vcc, s24, v64
	s_ashr_i32 s1, s0, 31
	s_nop 0
	v_addc_co_u32_e32 v67, vcc, 0, v65, vcc
	v_add_co_u32_e32 v104, vcc, s23, v64
	s_lshl_b64 s[0:1], s[0:1], 19
	s_nop 0
	v_addc_co_u32_e32 v105, vcc, 0, v65, vcc
	v_add_co_u32_e32 v112, vcc, s25, v64
	s_nop 1
	v_addc_co_u32_e32 v113, vcc, 0, v65, vcc
	v_add_co_u32_e32 v116, vcc, s26, v64
	s_nop 1
	v_addc_co_u32_e32 v117, vcc, 0, v65, vcc
	v_add_co_u32_e32 v120, vcc, s27, v64
	s_nop 1
	v_addc_co_u32_e32 v121, vcc, 0, v65, vcc
	v_add_co_u32_e32 v134, vcc, s28, v64
	s_nop 1
	v_addc_co_u32_e32 v135, vcc, 0, v65, vcc
	v_add_co_u32_e32 v64, vcc, s29, v64
	s_nop 1
	v_addc_co_u32_e32 v65, vcc, 0, v65, vcc
	global_load_dword v68, v80, s[12:13] offset:1024
	global_load_dword v139, v80, s[12:13] offset:2048
	global_load_dword v136, v80, s[12:13] offset:1088
	global_load_dword v137, v80, s[12:13] offset:2112
	global_load_dword v69, v80, s[12:13] offset:1152
	global_load_dword v70, v80, s[12:13] offset:2176
	global_load_dword v71, v80, s[12:13] offset:1216
	global_load_dword v72, v80, s[12:13] offset:192
	global_load_dword v151, v80, s[12:13] offset:3072
	global_load_dword v152, v[104:105], off offset:-4096
	global_load_dword v149, v[104:105], off
	global_load_dword v141, v80, s[12:13] offset:3136
	global_load_dword v140, v[104:105], off offset:64
	global_load_dword v84, v80, s[12:13] offset:3200
	global_load_dword v73, v80, s[12:13] offset:3264
	global_load_dword v74, v80, s[12:13] offset:2240
	global_load_dword v155, v[66:67], off offset:1024
	global_load_dword v156, v[66:67], off offset:2048
	global_load_dword v142, v[66:67], off offset:64
	global_load_dword v143, v[66:67], off offset:1088
	global_load_dword v87, v[66:67], off offset:128
	global_load_dword v88, v[66:67], off offset:1152
	global_load_dword v75, v[66:67], off offset:1216
	global_load_dword v76, v[66:67], off offset:192
	global_load_dword v159, v[66:67], off offset:3072
	global_load_dword v145, v[66:67], off offset:2112
	global_load_dword v146, v[66:67], off offset:3136
	global_load_dword v144, v[112:113], off offset:64
	global_load_dword v93, v[66:67], off offset:2176
	global_load_dword v94, v[66:67], off offset:3200
	global_load_dword v77, v[66:67], off offset:3264
	global_load_dword v78, v[66:67], off offset:2240
	global_load_dword v162, v[104:105], off offset:1024
	global_load_dword v163, v[104:105], off offset:2048
	global_load_dword v147, v[104:105], off offset:1088
	global_load_dword v148, v[104:105], off offset:2112
	global_load_dword v97, v[104:105], off offset:128
	global_load_dword v98, v[104:105], off offset:1152
	global_load_dword v79, v[104:105], off offset:1216
	global_load_dword v82, v[104:105], off offset:192
	global_load_dword v167, v[104:105], off offset:3072
	global_load_dword v168, v[116:117], off offset:-4096
	global_load_dword v164, v[116:117], off
	global_load_dword v150, v[104:105], off offset:3136
	global_load_dword v101, v[104:105], off offset:2176
	global_load_dword v102, v[104:105], off offset:3200
	global_load_dword v83, v[104:105], off offset:3264
	global_load_dword v85, v[104:105], off offset:2240
	global_load_dword v171, v[112:113], off offset:1024
	global_load_dword v172, v[112:113], off offset:2048
	global_load_dword v153, v[112:113], off offset:1088
	global_load_dword v154, v[112:113], off offset:2112
	s_nop 0
	global_load_dword v105, v[112:113], off offset:128
	global_load_dword v106, v[112:113], off offset:1152
	global_load_dword v86, v[112:113], off offset:1216
	global_load_dword v89, v[112:113], off offset:192
	global_load_dword v175, v[112:113], off offset:3072
	global_load_dword v158, v[112:113], off offset:3136
	global_load_dword v157, v[120:121], off offset:64
	global_load_dword v110, v[112:113], off offset:2176
	global_load_dword v111, v[112:113], off offset:3200
	global_load_dword v108, v[120:121], off offset:128
	global_load_dword v92, v[112:113], off offset:3264
	global_load_dword v95, v[112:113], off offset:2240
	global_load_dword v178, v[116:117], off offset:1024
	global_load_dword v179, v[116:117], off offset:2048
	global_load_dword v160, v[116:117], off offset:64
	global_load_dword v161, v[116:117], off offset:1088
	global_load_dword v114, v[116:117], off offset:128
	global_load_dword v115, v[116:117], off offset:1152
	global_load_dword v96, v[116:117], off offset:1216
	global_load_dword v99, v[116:117], off offset:192
	global_load_dword v182, v[116:117], off offset:3072
	global_load_dword v183, v[134:135], off offset:-4096
	global_load_dword v165, v[116:117], off offset:2112
	global_load_dword v166, v[116:117], off offset:3136
	global_load_dword v118, v[116:117], off offset:2176
	global_load_dword v119, v[116:117], off offset:3200
	global_load_dword v100, v[116:117], off offset:3264
	global_load_dword v103, v[116:117], off offset:2240
	global_load_dword v186, v[120:121], off offset:1024
	global_load_dword v187, v[120:121], off offset:2048
	global_load_dword v169, v[120:121], off offset:1088
	global_load_dword v170, v[120:121], off offset:2112
	global_load_dword v122, v[120:121], off offset:1152
	global_load_dword v123, v[120:121], off offset:2176
	global_load_dword v104, v[120:121], off offset:1216
	global_load_dword v107, v[120:121], off offset:192
	global_load_dword v190, v[120:121], off offset:3072
	global_load_dword v188, v[64:65], off
	global_load_dword v174, v[120:121], off offset:3136
	global_load_dword v173, v[64:65], off offset:64
	global_load_dword v127, v[120:121], off offset:3200
	global_load_dword v125, v[64:65], off offset:128
	global_load_dword v109, v[120:121], off offset:3264
	global_load_dword v112, v[120:121], off offset:2240
	global_load_dword v191, v[134:135], off
	global_load_dword v192, v[134:135], off offset:1024
	global_load_dword v176, v[134:135], off offset:64
	global_load_dword v177, v[134:135], off offset:1088
	global_load_dword v129, v[134:135], off offset:128
	global_load_dword v130, v[134:135], off offset:1152
	global_load_dword v113, v[134:135], off offset:1216
	global_load_dword v116, v[134:135], off offset:192
	global_load_dword v193, v[134:135], off offset:2048
	global_load_dword v194, v[134:135], off offset:3072
	global_load_dword v180, v[134:135], off offset:2112
	global_load_dword v181, v[134:135], off offset:3136
	global_load_dword v131, v[134:135], off offset:2176
	global_load_dword v132, v[134:135], off offset:3200
	global_load_dword v117, v[134:135], off offset:3264
	global_load_dword v120, v[134:135], off offset:2240
	global_load_dword v195, v[64:65], off offset:1024
	global_load_dword v196, v[64:65], off offset:2048
	global_load_dword v184, v[64:65], off offset:1088
	global_load_dword v185, v[64:65], off offset:2112
	global_load_dword v133, v[64:65], off offset:1152
	global_load_dword v134, v[64:65], off offset:2176
	global_load_dword v121, v[64:65], off offset:1216
	global_load_dword v124, v[64:65], off offset:192
	global_load_dword v199, v80, s[12:13]
	global_load_dword v197, v[64:65], off offset:3072
	global_load_dword v198, v80, s[12:13] offset:64
	global_load_dword v189, v[64:65], off offset:3136
	global_load_dword v138, v80, s[12:13] offset:128
	global_load_dword v135, v[64:65], off offset:3200
	global_load_dword v126, v[64:65], off offset:3264
	global_load_dword v128, v[64:65], off offset:2240
	v_ashrrev_i32_e32 v64, 1, v200
	v_and_b32_e32 v64, 0xffffffc0, v64
	v_lshrrev_b32_e32 v65, 2, v200
	v_add_u32_e32 v64, s14, v64
	v_and_or_b32 v64, v65, 12, v64
	s_add_u32 s12, s8, s0
	v_ashrrev_i32_e32 v65, 31, v64
	s_addc_u32 s13, s9, s1
	v_lshlrev_b64 v[66:67], 9, v[64:65]
	v_cmp_lt_i32_e32 vcc, s21, v64
	v_lshl_add_u64 v[66:67], s[12:13], 0, v[66:67]
	v_lshlrev_b32_e32 v80, 1, v201
	s_and_saveexec_b64 s[0:1], vcc
	s_xor_b64 s[0:1], exec, s[0:1]
	s_cbranch_execz .LBB0_972
	v_lshl_add_u64 v[200:201], v[66:67], 0, v[80:81]
	global_store_short v[200:201], v81, off

.LBB0_1794:
	s_ashr_i32 s0, s25, 3
	s_lshr_b32 s1, s0, 29
	s_add_i32 s1, s0, s1
	s_and_b32 s18, s1, 0x1fffff8
	s_sub_i32 s0, s0, s18
	s_lshl_b32 s1, s1, 8
	s_lshl_b32 s18, s25, 8
	s_and_b32 s1, s1, 0xfffff800
	s_and_b32 s18, s18, 0x700
	s_or_b32 s20, s1, s18
	s_ashr_i32 s21, s20, 31
	s_lshl_b32 s0, s0, 7
	s_lshl_b64 s[26:27], s[20:21], 12
	s_add_u32 s26, s3, s26
	s_addc_u32 s27, s4, s27
	s_ashr_i32 s1, s0, 31
	v_mov_b32_e32 v36, v220
	s_lshl_b64 s[28:29], s[0:1], 12
	s_add_u32 s28, s5, s28
	v_ashrrev_i32_e32 v26, 2, v36
	v_ashrrev_i32_e32 v27, 31, v26
	s_addc_u32 s29, s6, s29
	v_lshlrev_b64 v[0:1], 12, v[26:27]
	v_lshlrev_b32_e32 v4, 4, v36
	v_lshl_add_u64 v[2:3], s[28:29], 0, v[0:1]
	v_lshl_add_u64 v[0:1], s[26:27], 0, v[0:1]
	v_and_b32_e32 v176, 48, v4
	s_waitcnt vmcnt(9)
	v_lshl_add_u64 v[152:153], v[0:1], 0, v[176:177]
	v_add_co_u32_e32 v28, vcc, s7, v152
	v_lshl_add_u64 v[154:155], v[2:3], 0, v[176:177]
	s_nop 0
	v_addc_co_u32_e32 v29, vcc, 0, v153, vcc
	v_add_co_u32_e32 v30, vcc, s22, v152
	global_load_dwordx4 v[2:5], v[152:153], off
	s_nop 0
	v_addc_co_u32_e32 v31, vcc, 0, v153, vcc
	v_add_co_u32_e32 v32, vcc, s23, v152
	global_load_dwordx4 v[6:9], v[28:29], off
	s_nop 0
	v_addc_co_u32_e32 v33, vcc, 0, v153, vcc
	v_add_co_u32_e32 v34, vcc, s7, v154
	global_load_dwordx4 v[10:13], v[30:31], off
	s_nop 0
	v_addc_co_u32_e32 v35, vcc, 0, v155, vcc
	global_load_dwordx4 v[14:17], v[32:33], off
	global_load_dwordx4 v[18:21], v[154:155], off
	global_load_dwordx4 v[22:25], v[34:35], off
	global_load_dwordx4 v[112:115], v[152:153], off offset:64
	global_load_dwordx4 v[120:123], v[28:29], off offset:64
	global_load_dwordx4 v[124:127], v[30:31], off offset:64
	global_load_dwordx4 v[132:135], v[32:33], off offset:64
	global_load_dwordx4 v[128:131], v[154:155], off offset:64
	global_load_dwordx4 v[136:139], v[34:35], off offset:64
	v_lshrrev_b32_e32 v27, 4, v36
	v_lshrrev_b32_e32 v37, 2, v36
	v_sub_u32_e32 v40, 0, v27
	v_sub_u32_e32 v37, 0, v37
	v_and_b32_e32 v38, 0x3ffff8f, v36
	v_lshlrev_b32_e32 v39, 6, v36
	v_xor_b32_e32 v36, v36, v40
	v_xor_b32_e32 v27, v27, v37
	v_lshlrev_b32_e32 v36, 4, v36
	v_lshlrev_b32_e32 v27, 4, v27
	v_and_b32_e32 v41, 0x1000, v39
	v_and_b32_e32 v36, 48, v36
	v_and_b32_e32 v27, 48, v27
	v_and_b32_e32 v42, 0x3c0, v39
	v_and_b32_e32 v39, 0xffffe3c0, v39
	v_lshl_add_u32 v38, v38, 6, v198
	v_lshl_or_b32 v164, v26, 6, v36
	v_or_b32_e32 v26, v27, v41
	s_mov_b32 s1, -2
	s_mov_b32 s21, s19
	v_mov_b32_e32 v0, 0
	v_mov_b32_e32 v1, v177
	v_or3_b32 v165, v41, v42, v27
	v_add_u32_e32 v166, v27, v39
	v_add_u32_e32 v167, v27, v38
	v_add_u32_e32 v168, v26, v42
	v_lshl_add_u64 v[156:157], v[152:153], 0, s[12:13]
	v_lshl_add_u64 v[158:159], v[152:153], 0, s[14:15]
	v_lshl_add_u64 v[160:161], v[152:153], 0, s[16:17]
	v_lshl_add_u64 v[162:163], v[154:155], 0, s[12:13]
	v_mov_b32_e32 v26, v177
	v_mov_b32_e32 v27, v177
	v_mov_b32_e32 v28, 0
	v_mov_b32_e32 v29, v177
	v_mov_b32_e32 v30, v177
	v_mov_b32_e32 v31, v177
	v_mov_b32_e32 v32, 0
	v_mov_b32_e32 v33, v177
	v_mov_b32_e32 v34, v177
	v_mov_b32_e32 v35, v177
	v_mov_b32_e32 v36, 0
	v_mov_b32_e32 v37, v177
	v_mov_b32_e32 v38, v177
	v_mov_b32_e32 v39, v177
	v_mov_b32_e32 v40, 0
	v_mov_b32_e32 v41, v177
	v_mov_b32_e32 v42, v177
	v_mov_b32_e32 v43, v177
	v_mov_b32_e32 v44, 0
	s_waitcnt vmcnt(11)
	ds_write_b128 v164, v[2:5]
	s_waitcnt vmcnt(10)
	ds_write_b128 v164, v[6:9] offset:4096
	s_waitcnt vmcnt(9)
	ds_write_b128 v164, v[10:13] offset:8192
	s_waitcnt vmcnt(8)
	ds_write_b128 v164, v[14:17] offset:12288
	s_waitcnt vmcnt(7)
	ds_write_b128 v164, v[18:21] offset:32768
	s_waitcnt vmcnt(6)
	ds_write_b128 v164, v[22:25] offset:36864
	v_mov_b32_e32 v2, v177
	v_mov_b32_e32 v3, v177
	v_mov_b32_e32 v4, 0
	v_mov_b32_e32 v5, v177
	v_mov_b32_e32 v6, v177
	v_mov_b32_e32 v7, v177
	v_mov_b32_e32 v8, 0
	v_mov_b32_e32 v9, v177
	v_mov_b32_e32 v10, v177
	v_mov_b32_e32 v11, v177
	v_mov_b32_e32 v12, 0
	v_mov_b32_e32 v13, v177
	v_mov_b32_e32 v14, v177
	v_mov_b32_e32 v15, v177
	v_mov_b32_e32 v16, 0
	v_mov_b32_e32 v17, v177
	v_mov_b32_e32 v18, v177
	v_mov_b32_e32 v19, v177
	v_mov_b32_e32 v20, 0
	v_mov_b32_e32 v21, v177
	v_mov_b32_e32 v22, v177
	v_mov_b32_e32 v23, v177
	v_mov_b32_e32 v24, 0
	v_mov_b32_e32 v25, v177
	v_mov_b32_e32 v45, v177
	v_mov_b32_e32 v46, v177
	v_mov_b32_e32 v47, v177
	v_mov_b32_e32 v48, 0
	v_mov_b32_e32 v49, v177
	v_mov_b32_e32 v50, v177
	v_mov_b32_e32 v51, v177
	v_mov_b32_e32 v52, 0
	v_mov_b32_e32 v53, v177
	v_mov_b32_e32 v54, v177
	v_mov_b32_e32 v55, v177
	v_mov_b32_e32 v56, 0
	v_mov_b32_e32 v57, v177
	v_mov_b32_e32 v58, v177
	v_mov_b32_e32 v59, v177
	v_mov_b32_e32 v60, 0
	v_mov_b32_e32 v61, v177
	v_mov_b32_e32 v62, v177
	v_mov_b32_e32 v63, v177
	v_mov_b32_e32 v64, 0
	v_mov_b32_e32 v65, v177
	v_mov_b32_e32 v66, v177
	v_mov_b32_e32 v67, v177
	v_mov_b32_e32 v68, 0
	v_mov_b32_e32 v69, v177
	v_mov_b32_e32 v70, v177
	v_mov_b32_e32 v71, v177
	v_mov_b32_e32 v72, 0
	v_mov_b32_e32 v73, v177
	v_mov_b32_e32 v74, v177
	v_mov_b32_e32 v75, v177
	v_mov_b32_e32 v76, 0
	v_mov_b32_e32 v77, v177
	v_mov_b32_e32 v78, v177
	v_mov_b32_e32 v79, v177
	v_mov_b32_e32 v80, 0
	v_mov_b32_e32 v81, v177
	v_mov_b32_e32 v82, v177
	v_mov_b32_e32 v83, v177
	v_mov_b32_e32 v84, 0
	v_mov_b32_e32 v85, v177
	v_mov_b32_e32 v86, v177
	v_mov_b32_e32 v87, v177
	v_mov_b32_e32 v88, 0
	v_mov_b32_e32 v89, v177
	v_mov_b32_e32 v90, v177
	v_mov_b32_e32 v91, v177
	v_mov_b32_e32 v92, 0
	v_mov_b32_e32 v93, v177
	v_mov_b32_e32 v94, v177
	v_mov_b32_e32 v95, v177
	v_mov_b32_e32 v96, 0
	v_mov_b32_e32 v97, v177
	v_mov_b32_e32 v98, v177
	v_mov_b32_e32 v99, v177
	v_mov_b32_e32 v100, 0
	v_mov_b32_e32 v101, v177
	v_mov_b32_e32 v102, v177
	v_mov_b32_e32 v103, v177
	v_mov_b32_e32 v104, 0
	v_mov_b32_e32 v105, v177
	v_mov_b32_e32 v106, v177
	v_mov_b32_e32 v107, v177
	v_mov_b32_e32 v108, 0
	v_mov_b32_e32 v109, v177
	v_mov_b32_e32 v110, v177
	v_mov_b32_e32 v111, v177
	v_mov_b32_e32 v116, 0
	v_mov_b32_e32 v117, v177
	v_mov_b32_e32 v118, v177
	v_mov_b32_e32 v119, v177
	v_mov_b32_e32 v140, 0
	v_mov_b32_e32 v141, v177
	v_mov_b32_e32 v142, v177
	v_mov_b32_e32 v143, v177
	v_mov_b32_e32 v144, 0
	v_mov_b32_e32 v145, v177
	v_mov_b32_e32 v146, v177
	v_mov_b32_e32 v147, v177
	v_mov_b32_e32 v148, 0
	v_mov_b32_e32 v149, v177
	v_mov_b32_e32 v150, v177
	v_mov_b32_e32 v151, v177
	s_waitcnt lgkmcnt(0)
.Lrot2_1:
	s_barrier
.LBB0_1795:
	s_add_i32 s26, s21, 64
	s_min_u32 s18, s26, 0x7e0
	s_lshl_b32 s18, s18, 1
	v_lshl_add_u64 v[174:175], v[156:157], 0, s[18:19]
	global_load_dwordx4 v[178:181], v[174:175], off
	v_lshl_add_u64 v[174:175], v[158:159], 0, s[18:19]
	v_lshl_add_u64 v[170:171], v[152:153], 0, s[18:19]
	v_lshl_add_u64 v[186:187], v[160:161], 0, s[18:19]
	global_load_dwordx4 v[182:185], v[174:175], off
	v_lshl_add_u64 v[174:175], v[154:155], 0, s[18:19]
	v_lshl_add_u64 v[194:195], v[162:163], 0, s[18:19]
	global_load_dwordx4 v[170:173], v[170:171], off
	ds_read_b128 v[200:203], v168 offset:32768
	global_load_dwordx4 v[186:189], v[186:187], off
	ds_read_b128 v[204:207], v168 offset:33792
	global_load_dwordx4 v[190:193], v[174:175], off
	ds_read_b128 v[208:211], v168 offset:34816
	global_load_dwordx4 v[194:197], v[194:195], off
	ds_read_b128 v[212:215], v168 offset:35840
	ds_read_b128 v[216:219], v166
	ds_read_b128 v[222:225], v166 offset:1024
	ds_read_b128 v[226:229], v166 offset:2048
	ds_read_b128 v[230:233], v166 offset:3072
	ds_read_b128 v[234:237], v166 offset:4096
	ds_read_b128 v[238:241], v166 offset:5120
	ds_read_b128 v[242:245], v166 offset:6144
	ds_read_b128 v[246:249], v166 offset:7168
	s_setprio 1
	s_waitcnt lgkmcnt(7)
	v_mfma_f32_16x16x32_bf16 v[148:151], v[200:203], v[216:219], v[148:151]
	v_mfma_f32_16x16x32_bf16 v[144:147], v[204:207], v[216:219], v[144:147]
	v_mfma_f32_16x16x32_bf16 v[140:143], v[208:211], v[216:219], v[140:143]
	v_mfma_f32_16x16x32_bf16 v[116:119], v[212:215], v[216:219], v[116:119]
	s_waitcnt vmcnt(11)
	ds_write_b128 v164, v[112:115] offset:16384
	s_waitcnt lgkmcnt(7)
	v_mfma_f32_16x16x32_bf16 v[108:111], v[200:203], v[222:225], v[108:111]
	v_mfma_f32_16x16x32_bf16 v[104:107], v[204:207], v[222:225], v[104:107]
	v_mfma_f32_16x16x32_bf16 v[100:103], v[208:211], v[222:225], v[100:103]
	v_mfma_f32_16x16x32_bf16 v[96:99], v[212:215], v[222:225], v[96:99]
	s_waitcnt vmcnt(9)
	ds_write_b128 v164, v[120:123] offset:20480
	s_waitcnt lgkmcnt(7)
	v_mfma_f32_16x16x32_bf16 v[92:95], v[200:203], v[226:229], v[92:95]
	v_mfma_f32_16x16x32_bf16 v[88:91], v[204:207], v[226:229], v[88:91]
	v_mfma_f32_16x16x32_bf16 v[84:87], v[208:211], v[226:229], v[84:87]
	v_mfma_f32_16x16x32_bf16 v[80:83], v[212:215], v[226:229], v[80:83]
	s_waitcnt vmcnt(8)
	ds_write_b128 v164, v[124:127] offset:24576
	s_waitcnt lgkmcnt(7)
	v_mfma_f32_16x16x32_bf16 v[76:79], v[200:203], v[230:233], v[76:79]
	v_mfma_f32_16x16x32_bf16 v[72:75], v[204:207], v[230:233], v[72:75]
	v_mfma_f32_16x16x32_bf16 v[68:71], v[208:211], v[230:233], v[68:71]
	v_mfma_f32_16x16x32_bf16 v[64:67], v[212:215], v[230:233], v[64:67]
	s_waitcnt vmcnt(7)
	ds_write_b128 v164, v[132:135] offset:28672
	s_waitcnt lgkmcnt(7)
	v_mfma_f32_16x16x32_bf16 v[60:63], v[200:203], v[234:237], v[60:63]
	v_mfma_f32_16x16x32_bf16 v[56:59], v[204:207], v[234:237], v[56:59]
	v_mfma_f32_16x16x32_bf16 v[52:55], v[208:211], v[234:237], v[52:55]
	v_mfma_f32_16x16x32_bf16 v[48:51], v[212:215], v[234:237], v[48:51]
	s_waitcnt vmcnt(6)
	ds_write_b128 v164, v[136:139] offset:45056
	s_waitcnt lgkmcnt(7)
	v_mfma_f32_16x16x32_bf16 v[44:47], v[200:203], v[238:241], v[44:47]
	v_mfma_f32_16x16x32_bf16 v[40:43], v[204:207], v[238:241], v[40:43]
	v_mfma_f32_16x16x32_bf16 v[36:39], v[208:211], v[238:241], v[36:39]
	v_mfma_f32_16x16x32_bf16 v[32:35], v[212:215], v[238:241], v[32:35]
	ds_write_b128 v164, v[128:131] offset:40960
	s_waitcnt lgkmcnt(7)
	v_mfma_f32_16x16x32_bf16 v[28:31], v[200:203], v[242:245], v[28:31]
	v_mfma_f32_16x16x32_bf16 v[24:27], v[204:207], v[242:245], v[24:27]
	v_mfma_f32_16x16x32_bf16 v[20:23], v[208:211], v[242:245], v[20:23]
	v_mfma_f32_16x16x32_bf16 v[16:19], v[212:215], v[242:245], v[16:19]
	s_waitcnt lgkmcnt(6)
	v_mfma_f32_16x16x32_bf16 v[12:15], v[200:203], v[246:249], v[12:15]
	v_mfma_f32_16x16x32_bf16 v[8:11], v[204:207], v[246:249], v[8:11]
	v_mfma_f32_16x16x32_bf16 v[4:7], v[208:211], v[246:249], v[4:7]
	v_mfma_f32_16x16x32_bf16 v[0:3], v[212:215], v[246:249], v[0:3]
	s_setprio 0
	s_min_u32 s18, s21, 0x780
	s_lshl_b32 s18, s18, 1
	s_mov_b32 s29, s19
	s_add_i32 s28, s18, 0xc0
	v_lshl_add_u64 v[112:113], v[152:153], 0, s[18:19]
	v_lshl_add_u64 v[120:121], v[154:155], 0, s[18:19]
	v_lshl_add_u64 v[122:123], v[156:157], 0, s[28:29]
	v_lshl_add_u64 v[124:125], v[158:159], 0, s[28:29]
	v_lshl_add_u64 v[132:133], v[160:161], 0, s[28:29]
	v_lshl_add_u64 v[136:137], v[162:163], 0, s[28:29]
	s_waitcnt lgkmcnt(0)
	s_barrier
	global_load_dwordx4 v[112:115], v[112:113], off offset:192
	ds_read_b128 v[200:203], v165 offset:40960
	global_load_dwordx4 v[128:131], v[120:121], off offset:192
	ds_read_b128 v[204:207], v165 offset:41984
	global_load_dwordx4 v[120:123], v[122:123], off
	ds_read_b128 v[208:211], v165 offset:43008
	global_load_dwordx4 v[124:127], v[124:125], off
	ds_read_b128 v[212:215], v165 offset:44032
	global_load_dwordx4 v[132:135], v[132:133], off
	ds_read_b128 v[216:219], v167
	global_load_dwordx4 v[136:139], v[136:137], off
	ds_read_b128 v[222:225], v167 offset:1024
	ds_read_b128 v[226:229], v167 offset:2048
	ds_read_b128 v[230:233], v167 offset:3072
	ds_read_b128 v[234:237], v167 offset:4096
	ds_read_b128 v[238:241], v167 offset:5120
	ds_read_b128 v[242:245], v167 offset:6144
	ds_read_b128 v[246:249], v167 offset:7168
	s_setprio 1
	s_waitcnt lgkmcnt(7)
	v_mfma_f32_16x16x32_bf16 v[148:151], v[200:203], v[216:219], v[148:151]
	v_mfma_f32_16x16x32_bf16 v[144:147], v[204:207], v[216:219], v[144:147]
	v_mfma_f32_16x16x32_bf16 v[140:143], v[208:211], v[216:219], v[140:143]
	v_mfma_f32_16x16x32_bf16 v[116:119], v[212:215], v[216:219], v[116:119]
	s_waitcnt vmcnt(9)
	ds_write_b128 v164, v[170:173]
	s_waitcnt lgkmcnt(7)
	v_mfma_f32_16x16x32_bf16 v[108:111], v[200:203], v[222:225], v[108:111]
	v_mfma_f32_16x16x32_bf16 v[104:107], v[204:207], v[222:225], v[104:107]
	v_mfma_f32_16x16x32_bf16 v[100:103], v[208:211], v[222:225], v[100:103]
	v_mfma_f32_16x16x32_bf16 v[96:99], v[212:215], v[222:225], v[96:99]
	ds_write_b128 v164, v[178:181] offset:4096
	s_waitcnt lgkmcnt(7)
	v_mfma_f32_16x16x32_bf16 v[92:95], v[200:203], v[226:229], v[92:95]
	v_mfma_f32_16x16x32_bf16 v[88:91], v[204:207], v[226:229], v[88:91]
	v_mfma_f32_16x16x32_bf16 v[84:87], v[208:211], v[226:229], v[84:87]
	v_mfma_f32_16x16x32_bf16 v[80:83], v[212:215], v[226:229], v[80:83]
	ds_write_b128 v164, v[182:185] offset:8192
	s_waitcnt lgkmcnt(7)
	v_mfma_f32_16x16x32_bf16 v[76:79], v[200:203], v[230:233], v[76:79]
	v_mfma_f32_16x16x32_bf16 v[72:75], v[204:207], v[230:233], v[72:75]
	v_mfma_f32_16x16x32_bf16 v[68:71], v[208:211], v[230:233], v[68:71]
	v_mfma_f32_16x16x32_bf16 v[64:67], v[212:215], v[230:233], v[64:67]
	s_waitcnt vmcnt(8)
	ds_write_b128 v164, v[186:189] offset:12288
	s_waitcnt lgkmcnt(7)
	v_mfma_f32_16x16x32_bf16 v[60:63], v[200:203], v[234:237], v[60:63]
	v_mfma_f32_16x16x32_bf16 v[56:59], v[204:207], v[234:237], v[56:59]
	v_mfma_f32_16x16x32_bf16 v[52:55], v[208:211], v[234:237], v[52:55]
	v_mfma_f32_16x16x32_bf16 v[48:51], v[212:215], v[234:237], v[48:51]
	s_waitcnt vmcnt(7)
	ds_write_b128 v164, v[190:193] offset:32768
	s_waitcnt lgkmcnt(7)
	v_mfma_f32_16x16x32_bf16 v[44:47], v[200:203], v[238:241], v[44:47]
	v_mfma_f32_16x16x32_bf16 v[40:43], v[204:207], v[238:241], v[40:43]
	v_mfma_f32_16x16x32_bf16 v[36:39], v[208:211], v[238:241], v[36:39]
	v_mfma_f32_16x16x32_bf16 v[32:35], v[212:215], v[238:241], v[32:35]
	s_waitcnt vmcnt(6)
	ds_write_b128 v164, v[194:197] offset:36864
	s_waitcnt lgkmcnt(7)
	v_mfma_f32_16x16x32_bf16 v[28:31], v[200:203], v[242:245], v[28:31]
	v_mfma_f32_16x16x32_bf16 v[24:27], v[204:207], v[242:245], v[24:27]
	v_mfma_f32_16x16x32_bf16 v[20:23], v[208:211], v[242:245], v[20:23]
	v_mfma_f32_16x16x32_bf16 v[16:19], v[212:215], v[242:245], v[16:19]
	s_waitcnt lgkmcnt(6)
	v_mfma_f32_16x16x32_bf16 v[12:15], v[200:203], v[246:249], v[12:15]
	v_mfma_f32_16x16x32_bf16 v[8:11], v[204:207], v[246:249], v[8:11]
	v_mfma_f32_16x16x32_bf16 v[4:7], v[208:211], v[246:249], v[4:7]
	v_mfma_f32_16x16x32_bf16 v[0:3], v[212:215], v[246:249], v[0:3]
	s_setprio 0
	s_add_i32 s1, s1, 2
	s_cmp_lt_u32 s1, 62
	s_mov_b32 s21, s26
	s_waitcnt lgkmcnt(0)
	s_cbranch_scc1 .Lrot2_1
	s_barrier
	s_waitcnt vmcnt(5)
	v_mov_b32_e32 v112, v220
	s_nop 0
	v_and_b32_e32 v114, 0xffffff80, v112
	v_bfe_u32 v176, v112, 4, 2
	v_add_u32_e32 v114, s20, v114
	v_and_b32_e32 v113, 64, v112
	v_and_or_b32 v184, v112, 15, v114
	v_lshlrev_b32_e32 v112, 2, v176
	v_or3_b32 v178, v112, v113, s0
	v_ashrrev_i32_e32 v179, 31, v178
	v_lshlrev_b64 v[216:217], 2, v[178:179]
	v_ashrrev_i32_e32 v185, 31, v184
	v_or_b32_e32 v194, 16, v184
	v_lshl_add_u64 v[182:183], s[70:71], 0, v[216:217]
	v_lshlrev_b64 v[218:219], 12, v[184:185]
	v_ashrrev_i32_e32 v195, 31, v194
	v_or_b32_e32 v190, 32, v184
	v_lshl_add_u64 v[112:113], v[182:183], 0, v[218:219]
	v_lshlrev_b64 v[196:197], 12, v[194:195]
	v_ashrrev_i32_e32 v191, 31, v190
	v_or_b32_e32 v186, 48, v184
	global_load_dwordx4 v[200:203], v[112:113], off
	global_load_dwordx4 v[204:207], v[112:113], off offset:64
	global_load_dwordx4 v[208:211], v[112:113], off offset:128
	global_load_dwordx4 v[212:215], v[112:113], off offset:192
	v_lshl_add_u64 v[112:113], v[182:183], 0, v[196:197]
	v_lshlrev_b64 v[192:193], 12, v[190:191]
	v_ashrrev_i32_e32 v187, 31, v186
	global_load_dwordx4 v[172:175], v[112:113], off
	global_load_dwordx4 v[168:171], v[112:113], off offset:64
	global_load_dwordx4 v[164:167], v[112:113], off offset:128
	global_load_dwordx4 v[160:163], v[112:113], off offset:192
	v_lshl_add_u64 v[112:113], v[182:183], 0, v[192:193]
	v_lshlrev_b64 v[188:189], 12, v[186:187]
	global_load_dwordx4 v[156:159], v[112:113], off
	global_load_dwordx4 v[152:155], v[112:113], off offset:64
	global_load_dwordx4 v[136:139], v[112:113], off offset:128
	global_load_dwordx4 v[132:135], v[112:113], off offset:192
	v_lshl_add_u64 v[112:113], v[182:183], 0, v[188:189]
	global_load_dwordx4 v[128:131], v[112:113], off
	global_load_dwordx4 v[124:127], v[112:113], off offset:64
	global_load_dwordx4 v[120:123], v[112:113], off offset:128
	s_nop 0
	global_load_dwordx4 v[112:115], v[112:113], off offset:192
	v_cmp_eq_u32_e32 vcc, 0, v176
	v_lshlrev_b64 v[222:223], 11, v[184:185]
	v_lshlrev_b64 v[180:181], 1, v[178:179]
	v_lshl_add_u64 v[218:219], s[70:71], 0, v[218:219]
	v_lshl_add_u64 v[224:225], s[8:9], 0, v[222:223]
	v_lshl_add_u64 v[216:217], v[218:219], 0, v[216:217]
	v_lshl_add_u64 v[218:219], v[224:225], 0, v[180:181]
	v_lshl_add_u64 v[222:223], s[72:73], 0, v[222:223]
	v_lshl_add_u64 v[222:223], v[222:223], 0, v[180:181]
	s_waitcnt vmcnt(15)
	v_pk_add_f32 v[148:149], v[148:149], v[200:201]
	s_waitcnt vmcnt(14)
	v_pk_add_f32 v[144:145], v[144:145], v[204:205]
	v_pk_add_f32 v[146:147], v[146:147], v[206:207]
	s_waitcnt vmcnt(13)
	v_pk_add_f32 v[140:141], v[140:141], v[208:209]
	v_mul_f32_e32 v176, v149, v149
	v_mul_f32_e32 v206, v145, v145
	v_pk_add_f32 v[150:151], v[150:151], v[202:203]
	s_waitcnt vmcnt(12)
	v_pk_add_f32 v[116:117], v[116:117], v[212:213]
	v_mul_f32_e32 v212, v141, v141
	v_pk_fma_f32 v[226:227], v[148:149], v[148:149], v[176:177] op_sel_hi:[1,1,0]
	v_pk_fma_f32 v[206:207], v[144:145], v[144:145], v[206:207] op_sel_hi:[1,1,0]
	v_pk_add_f32 v[142:143], v[142:143], v[210:211]
	v_mul_f32_e32 v202, v151, v151
	v_mul_f32_e32 v208, v147, v147
	v_pk_fma_f32 v[212:213], v[140:141], v[140:141], v[212:213] op_sel_hi:[1,1,0]
	v_pk_fma_f32 v[226:227], v[150:151], v[150:151], v[226:227]
	v_pk_fma_f32 v[206:207], v[146:147], v[146:147], v[206:207]
	v_mul_f32_e32 v224, v143, v143
	v_pk_fma_f32 v[212:213], v[142:143], v[142:143], v[212:213]
	v_pk_add_f32 v[202:203], v[202:203], v[226:227] op_sel_hi:[0,1]
	v_pk_add_f32 v[206:207], v[208:209], v[206:207] op_sel_hi:[0,1]
	v_pk_add_f32 v[208:209], v[224:225], v[212:213] op_sel_hi:[0,1]
	v_pk_add_f32 v[202:203], v[202:203], v[206:207]
	v_cvt_pk_bf16_f32 v200, v148, v149
	v_cvt_pk_bf16_f32 v201, v150, v151
	v_cvt_pk_bf16_f32 v204, v144, v145
	v_cvt_pk_bf16_f32 v205, v146, v147
	v_cvt_pk_bf16_f32 v210, v140, v141
	v_cvt_pk_bf16_f32 v211, v142, v143
	s_nop 0
	v_pk_add_f32 v[202:203], v[202:203], v[208:209]
	v_pk_add_f32 v[118:119], v[118:119], v[214:215]
	global_store_dwordx4 v[216:217], v[148:151], off
	global_store_dwordx2 v[218:219], v[200:201], off
	global_store_dwordx4 v[216:217], v[144:147], off offset:64
	s_nop 1
	v_add_co_u32_e64 v144, s[0:1], s24, v222
	s_nop 1
	v_addc_co_u32_e64 v145, s[0:1], 0, v223, s[0:1]
	global_store_dwordx2 v[144:145], v[204:205], off offset:32
	global_store_dwordx4 v[216:217], v[140:143], off offset:128
	global_store_dwordx2 v[144:145], v[210:211], off offset:64
	global_store_dwordx4 v[216:217], v[116:119], off offset:192
	v_cvt_pk_bf16_f32 v140, v116, v117
	v_cvt_pk_bf16_f32 v141, v118, v119
	global_store_dwordx2 v[144:145], v[140:141], off offset:96
	v_mul_f32_e32 v140, v117, v117
	v_pk_fma_f32 v[116:117], v[116:117], v[116:117], v[140:141] op_sel_hi:[1,1,0]
	s_nop 0
	v_pk_fma_f32 v[116:117], v[118:119], v[118:119], v[116:117]
	v_mul_f32_e32 v118, v119, v119
	v_pk_add_f32 v[116:117], v[118:119], v[116:117] op_sel_hi:[0,1]
	v_pk_add_f32 v[116:117], v[202:203], v[116:117]
	s_nop 0
	v_mov_b32_e32 v117, v116
	s_nop 1
	v_permlane32_swap_b32_e32 v116, v117
	v_add_f32_e32 v116, v116, v117
	v_mov_b32_e32 v117, v116
	s_nop 1
	v_permlane16_swap_b32_e32 v116, v117
	s_and_saveexec_b64 s[0:1], vcc
	s_cbranch_execz .LBB0_1798
	v_lshl_add_u64 v[118:119], v[184:185], 2, s[10:11]
	v_add_f32_e32 v116, v116, v117
	global_atomic_add_f32 v[118:119], v116, off

.LBB0_1867:
	s_min_u32 s24, s22, 0xe0
	s_lshl_b32 s6, s24, 2
	v_lshl_add_u64 v[94:95], v[70:71], 0, s[6:7]
	v_lshl_add_u64 v[96:97], v[72:73], 0, s[6:7]
	s_lshl_b32 s6, s24, 1
	v_lshl_add_u64 v[102:103], v[66:67], 0, s[6:7]
	v_lshl_add_u64 v[104:105], v[68:69], 0, s[6:7]
	global_load_dwordx4 v[78:81], v[94:95], off offset:16 nt
	global_load_dwordx4 v[82:85], v[94:95], off nt
	global_load_dwordx4 v[86:89], v[96:97], off offset:16 nt
	global_load_dwordx4 v[90:93], v[96:97], off nt
	global_load_dwordx4 v[98:101], v[104:105], off
	s_and_b32 s6, s23, 0x80
	global_load_dwordx4 v[94:97], v[102:103], off
	v_add_u32_e32 v77, s6, v74
	v_or_b32_e32 v102, s6, v76
	v_lshl_or_b32 v77, v77, 6, v75
	v_lshl_or_b32 v130, v102, 6, v75
	ds_read_b128 v[102:105], v77
	ds_read_b128 v[106:109], v77 offset:1024
	ds_read_b128 v[110:113], v130 offset:16384
	ds_read_b128 v[114:117], v130 offset:17408
	ds_read_b128 v[118:121], v77 offset:2048
	ds_read_b128 v[122:125], v77 offset:3072
	ds_read_b128 v[126:129], v130 offset:18432
	ds_read_b128 v[130:133], v130 offset:19456
	s_setprio 1
	s_waitcnt lgkmcnt(5)
	v_mfma_f32_16x16x32_bf16 v[52:55], v[110:113], v[102:105], v[52:55]
	s_waitcnt lgkmcnt(4)
	v_mfma_f32_16x16x32_bf16 v[48:51], v[114:117], v[102:105], v[48:51]
	s_waitcnt lgkmcnt(1)
	v_mfma_f32_16x16x32_bf16 v[40:43], v[126:129], v[102:105], v[40:43]
	s_waitcnt lgkmcnt(0)
	v_mfma_f32_16x16x32_bf16 v[20:23], v[130:133], v[102:105], v[20:23]
	v_mfma_f32_16x16x32_bf16 v[44:47], v[110:113], v[106:109], v[44:47]
	v_mfma_f32_16x16x32_bf16 v[36:39], v[114:117], v[106:109], v[36:39]
	v_mfma_f32_16x16x32_bf16 v[28:31], v[126:129], v[106:109], v[28:31]
	v_mfma_f32_16x16x32_bf16 v[16:19], v[130:133], v[106:109], v[16:19]
	v_mfma_f32_16x16x32_bf16 v[32:35], v[110:113], v[118:121], v[32:35]
	v_mfma_f32_16x16x32_bf16 v[24:27], v[114:117], v[118:121], v[24:27]
	v_mfma_f32_16x16x32_bf16 v[12:15], v[126:129], v[118:121], v[12:15]
	v_mfma_f32_16x16x32_bf16 v[8:11], v[130:133], v[118:121], v[8:11]
	v_mfma_f32_16x16x32_bf16 v[60:63], v[110:113], v[122:125], v[60:63]
	v_mfma_f32_16x16x32_bf16 v[56:59], v[114:117], v[122:125], v[56:59]
	v_mfma_f32_16x16x32_bf16 v[4:7], v[126:129], v[122:125], v[4:7]
	v_mfma_f32_16x16x32_bf16 v[0:3], v[130:133], v[122:125], v[0:3]
	s_setprio 0
	s_waitcnt vmcnt(4)
	v_and_b32_sdwa v102, v84, v155 dst_sel:DWORD dst_unused:UNUSED_PAD src0_sel:WORD_1 src1_sel:DWORD
	v_and_b32_sdwa v103, v82, v155 dst_sel:DWORD dst_unused:UNUSED_PAD src0_sel:WORD_1 src1_sel:DWORD
	v_add3_u32 v84, v84, v102, s17
	v_and_b32_sdwa v102, v85, v155 dst_sel:DWORD dst_unused:UNUSED_PAD src0_sel:WORD_1 src1_sel:DWORD
	v_add3_u32 v82, v82, v103, s17
	v_and_b32_sdwa v103, v83, v155 dst_sel:DWORD dst_unused:UNUSED_PAD src0_sel:WORD_1 src1_sel:DWORD
	v_add3_u32 v85, v85, v102, s17
	v_add3_u32 v83, v83, v103, s17
	v_and_b32_e32 v85, 0xffff0000, v85
	v_and_b32_e32 v102, 0xffff0000, v83
	v_or_b32_sdwa v83, v85, v84 dst_sel:DWORD dst_unused:UNUSED_PAD src0_sel:DWORD src1_sel:WORD_1
	v_and_b32_sdwa v85, v78, v155 dst_sel:DWORD dst_unused:UNUSED_PAD src0_sel:WORD_1 src1_sel:DWORD
	v_and_b32_sdwa v84, v80, v155 dst_sel:DWORD dst_unused:UNUSED_PAD src0_sel:WORD_1 src1_sel:DWORD
	v_add3_u32 v78, v78, v85, s17
	v_and_b32_sdwa v85, v79, v155 dst_sel:DWORD dst_unused:UNUSED_PAD src0_sel:WORD_1 src1_sel:DWORD
	v_add3_u32 v80, v80, v84, s17
	v_and_b32_sdwa v84, v81, v155 dst_sel:DWORD dst_unused:UNUSED_PAD src0_sel:WORD_1 src1_sel:DWORD
	v_add3_u32 v79, v79, v85, s17
	v_add3_u32 v81, v81, v84, s17
	v_and_b32_e32 v79, 0xffff0000, v79
	v_and_b32_e32 v81, 0xffff0000, v81
	v_or_b32_sdwa v84, v79, v78 dst_sel:DWORD dst_unused:UNUSED_PAD src0_sel:DWORD src1_sel:WORD_1
	s_waitcnt vmcnt(2)
	v_and_b32_sdwa v79, v90, v155 dst_sel:DWORD dst_unused:UNUSED_PAD src0_sel:WORD_1 src1_sel:DWORD
	v_or_b32_sdwa v85, v81, v80 dst_sel:DWORD dst_unused:UNUSED_PAD src0_sel:DWORD src1_sel:WORD_1
	v_add3_u32 v80, v90, v79, s17
	v_and_b32_sdwa v79, v93, v155 dst_sel:DWORD dst_unused:UNUSED_PAD src0_sel:WORD_1 src1_sel:DWORD
	v_and_b32_sdwa v81, v91, v155 dst_sel:DWORD dst_unused:UNUSED_PAD src0_sel:WORD_1 src1_sel:DWORD
	s_xor_b32 s6, s6, 0x80
	v_and_b32_sdwa v78, v92, v155 dst_sel:DWORD dst_unused:UNUSED_PAD src0_sel:WORD_1 src1_sel:DWORD
	v_add3_u32 v79, v93, v79, s17
	v_add3_u32 v81, v91, v81, s17
	v_add_u32_e32 v77, s6, v64
	v_add3_u32 v78, v92, v78, s17
	v_and_b32_e32 v79, 0xffff0000, v79
	v_and_b32_e32 v81, 0xffff0000, v81
	v_lshl_or_b32 v77, v77, 6, v65
	v_or_b32_sdwa v82, v102, v82 dst_sel:DWORD dst_unused:UNUSED_PAD src0_sel:DWORD src1_sel:WORD_1
	v_or_b32_sdwa v79, v79, v78 dst_sel:DWORD dst_unused:UNUSED_PAD src0_sel:DWORD src1_sel:WORD_1
	v_or_b32_sdwa v78, v81, v80 dst_sel:DWORD dst_unused:UNUSED_PAD src0_sel:DWORD src1_sel:WORD_1
	v_and_b32_sdwa v81, v86, v155 dst_sel:DWORD dst_unused:UNUSED_PAD src0_sel:WORD_1 src1_sel:DWORD
	ds_write_b128 v77, v[82:85]
	v_add3_u32 v82, v86, v81, s17
	v_and_b32_sdwa v81, v89, v155 dst_sel:DWORD dst_unused:UNUSED_PAD src0_sel:WORD_1 src1_sel:DWORD
	v_and_b32_sdwa v83, v87, v155 dst_sel:DWORD dst_unused:UNUSED_PAD src0_sel:WORD_1 src1_sel:DWORD
	v_and_b32_sdwa v80, v88, v155 dst_sel:DWORD dst_unused:UNUSED_PAD src0_sel:WORD_1 src1_sel:DWORD
	v_add3_u32 v81, v89, v81, s17
	v_add3_u32 v83, v87, v83, s17
	v_add3_u32 v80, v88, v80, s17
	v_and_b32_e32 v81, 0xffff0000, v81
	v_and_b32_e32 v83, 0xffff0000, v83
	s_addk_i32 s23, 0x80
	s_add_i32 s22, s22, 32
	v_or_b32_sdwa v81, v81, v80 dst_sel:DWORD dst_unused:UNUSED_PAD src0_sel:DWORD src1_sel:WORD_1
	v_or_b32_sdwa v80, v83, v82 dst_sel:DWORD dst_unused:UNUSED_PAD src0_sel:DWORD src1_sel:WORD_1
	s_cmpk_lg_i32 s23, 0x400
	ds_write_b128 v77, v[78:81] offset:4096
	s_waitcnt vmcnt(0)
	ds_write_b128 v77, v[94:97] offset:16384
	ds_write_b128 v77, v[98:101] offset:20480
	s_waitcnt lgkmcnt(0)
	s_barrier
	s_cbranch_scc1 .LBB0_1867
	s_lshl_b64 s[22:23], s[10:11], 11
	v_mov_b32_e32 v106, v220
	s_add_u32 s22, s13, s22
	s_addc_u32 s23, s14, s23
	v_ashrrev_i32_e32 v102, 2, v106
	s_lshl_b64 s[24:25], s[8:9], 11
	v_add_u32_e32 v104, 64, v102
	s_add_u32 s24, s15, s24
	v_ashrrev_i32_e32 v105, 31, v104
	s_addc_u32 s25, s16, s25
	v_lshlrev_b64 v[64:65], 11, v[104:105]
	v_min_i32_e32 v66, 0x7f, v102
	v_lshlrev_b32_e32 v67, 4, v106
	v_lshl_add_u64 v[64:65], s[24:25], 0, v[64:65]
	v_and_b32_e32 v144, 48, v67
	v_ashrrev_i32_e32 v67, 31, v66
	v_ashrrev_i32_e32 v103, 31, v102
	v_min_i32_e32 v68, 0x7f, v104
	v_lshl_add_u64 v[148:149], v[64:65], 0, v[144:145]
	v_lshlrev_b64 v[64:65], 11, v[66:67]
	v_lshlrev_b64 v[70:71], 11, v[102:103]
	v_lshl_add_u64 v[64:65], s[22:23], 0, v[64:65]
	v_ashrrev_i32_e32 v69, 31, v68
	v_lshl_add_u64 v[70:71], s[24:25], 0, v[70:71]
	v_lshl_add_u64 v[150:151], v[64:65], 0, v[144:145]
	v_lshlrev_b64 v[64:65], 11, v[68:69]
	v_lshl_add_u64 v[146:147], v[70:71], 0, v[144:145]
	v_lshl_add_u64 v[64:65], s[22:23], 0, v[64:65]
	global_load_dwordx4 v[86:89], v[150:151], off
	global_load_dwordx4 v[90:93], v[146:147], off
	v_lshl_add_u64 v[152:153], v[64:65], 0, v[144:145]
	global_load_dwordx4 v[94:97], v[148:149], off
	global_load_dwordx4 v[98:101], v[152:153], off
	global_load_dwordx4 v[124:127], v[146:147], off offset:64
	global_load_dwordx4 v[128:131], v[150:151], off offset:64
	global_load_dwordx4 v[132:135], v[148:149], off offset:64
	global_load_dwordx4 v[136:139], v[152:153], off offset:64
	v_lshrrev_b32_e32 v103, 4, v106
	v_lshrrev_b32_e32 v105, 2, v106
	v_sub_u32_e32 v110, 0, v103
	v_and_b32_e32 v107, 15, v106
	v_lshrrev_b32_e32 v108, 1, v106
	v_lshlrev_b32_e32 v109, 6, v106
	v_sub_u32_e32 v105, 0, v105
	v_xor_b32_e32 v106, v106, v110
	v_and_or_b32 v107, v108, s19, v107
	v_xor_b32_e32 v103, v103, v105
	v_lshlrev_b32_e32 v105, 4, v106
	v_lshlrev_b32_e32 v156, 6, v107
	v_lshlrev_b32_e32 v103, 4, v103
	v_and_b32_e32 v105, 48, v105
	v_mov_b32_e32 v64, 0
	v_and_b32_e32 v144, 0x13c0, v109
	v_add_u32_e32 v106, 0x2000, v156
	v_and_b32_e32 v157, 48, v103
	v_lshl_or_b32 v158, v102, 6, v105
	s_mov_b32 s11, 0
	s_mov_b32 s9, -2
	v_mov_b32_e32 v65, v64
	v_mov_b32_e32 v66, v64
	v_mov_b32_e32 v67, v64
	v_mov_b32_e32 v68, v64
	v_mov_b32_e32 v69, v64
	v_mov_b32_e32 v70, v64
	v_mov_b32_e32 v71, v64
	v_mov_b32_e32 v72, v64
	v_mov_b32_e32 v73, v64
	v_mov_b32_e32 v74, v64
	v_mov_b32_e32 v75, v64
	v_mov_b32_e32 v76, v64
	v_mov_b32_e32 v77, v64
	v_mov_b32_e32 v78, v64
	v_mov_b32_e32 v79, v64
	v_mov_b32_e32 v80, v64
	v_mov_b32_e32 v81, v64
	v_mov_b32_e32 v82, v64
	v_mov_b32_e32 v83, v64
	v_mov_b32_e32 v84, v64
	v_mov_b32_e32 v85, v64
	v_lshl_or_b32 v159, v104, 6, v105
	v_or_b32_e32 v160, v157, v144
	v_add_u32_e32 v161, v157, v106
	v_mov_b32_e32 v102, v64
	v_mov_b32_e32 v103, v64
	v_mov_b32_e32 v104, v64
	v_mov_b32_e32 v105, v64
	v_mov_b32_e32 v106, v64
	v_mov_b32_e32 v107, v64
	v_mov_b32_e32 v108, v64
	v_mov_b32_e32 v109, v64
	v_mov_b32_e32 v110, v64
	v_mov_b32_e32 v111, v64
	v_mov_b32_e32 v112, v64
	s_waitcnt vmcnt(6)
	ds_write_b128 v158, v[90:93] offset:16384
	ds_write_b128 v158, v[86:89]
	s_waitcnt vmcnt(5)
	ds_write_b128 v159, v[94:97] offset:16384
	s_waitcnt vmcnt(4)
	ds_write_b128 v159, v[98:101]
	v_mov_b32_e32 v86, v64
	v_mov_b32_e32 v87, v64
	v_mov_b32_e32 v88, v64
	v_mov_b32_e32 v89, v64
	v_mov_b32_e32 v90, v64
	v_mov_b32_e32 v91, v64
	v_mov_b32_e32 v92, v64
	v_mov_b32_e32 v93, v64
	v_mov_b32_e32 v94, v64
	v_mov_b32_e32 v95, v64
	v_mov_b32_e32 v96, v64
	v_mov_b32_e32 v97, v64
	v_mov_b32_e32 v98, v64
	v_mov_b32_e32 v99, v64
	v_mov_b32_e32 v100, v64
	v_mov_b32_e32 v101, v64
	v_mov_b32_e32 v113, v64
	v_mov_b32_e32 v114, v64
	v_mov_b32_e32 v115, v64
	v_mov_b32_e32 v116, v64
	v_mov_b32_e32 v117, v64
	v_mov_b32_e32 v118, v64
	v_mov_b32_e32 v119, v64
	v_mov_b32_e32 v120, v64
	v_mov_b32_e32 v121, v64
	v_mov_b32_e32 v122, v64
	v_mov_b32_e32 v123, v64
	v_mov_b32_e32 v140, v64
	v_mov_b32_e32 v141, v64
	v_mov_b32_e32 v142, v64
	v_mov_b32_e32 v143, v64
	s_waitcnt lgkmcnt(0)
.Lrot2_0:
	s_barrier
.LBB0_1869:
	s_add_i32 s22, s11, 64
	s_min_u32 s6, s22, 0x3e0
	s_lshl_b32 s6, s6, 1
	v_lshl_add_u64 v[162:163], v[150:151], 0, s[6:7]
	v_lshl_add_u64 v[166:167], v[152:153], 0, s[6:7]
	v_lshl_add_u64 v[170:171], v[146:147], 0, s[6:7]
	v_lshl_add_u64 v[174:175], v[148:149], 0, s[6:7]
	global_load_dwordx4 v[162:165], v[162:163], off
	v_add_u32_e32 v198, v157, v156
	global_load_dwordx4 v[166:169], v[166:167], off
	v_add_u32_e32 v206, v157, v144
	global_load_dwordx4 v[170:173], v[170:171], off
	ds_read_b128 v[178:181], v198
	global_load_dwordx4 v[174:177], v[174:175], off
	ds_read_b128 v[182:185], v198 offset:1024
	ds_read_b128 v[186:189], v206 offset:16384
	ds_read_b128 v[190:193], v206 offset:17408
	ds_read_b128 v[194:197], v198 offset:2048
	ds_read_b128 v[198:201], v198 offset:3072
	ds_read_b128 v[202:205], v206 offset:18432
	ds_read_b128 v[206:209], v206 offset:19456
	s_setprio 1
	s_waitcnt lgkmcnt(5)
	v_mfma_f32_16x16x32_bf16 v[140:143], v[186:189], v[178:181], v[140:143]
	s_waitcnt lgkmcnt(4)
	v_mfma_f32_16x16x32_bf16 v[120:123], v[190:193], v[178:181], v[120:123]
	s_waitcnt lgkmcnt(1)
	v_mfma_f32_16x16x32_bf16 v[116:119], v[202:205], v[178:181], v[116:119]
	s_waitcnt lgkmcnt(0)
	v_mfma_f32_16x16x32_bf16 v[112:115], v[206:209], v[178:181], v[112:115]
	v_mfma_f32_16x16x32_bf16 v[108:111], v[186:189], v[182:185], v[108:111]
	v_mfma_f32_16x16x32_bf16 v[104:107], v[190:193], v[182:185], v[104:107]
	v_mfma_f32_16x16x32_bf16 v[100:103], v[202:205], v[182:185], v[100:103]
	v_mfma_f32_16x16x32_bf16 v[96:99], v[206:209], v[182:185], v[96:99]
	v_mfma_f32_16x16x32_bf16 v[92:95], v[186:189], v[194:197], v[92:95]
	v_mfma_f32_16x16x32_bf16 v[88:91], v[190:193], v[194:197], v[88:91]
	v_mfma_f32_16x16x32_bf16 v[84:87], v[202:205], v[194:197], v[84:87]
	v_mfma_f32_16x16x32_bf16 v[80:83], v[206:209], v[194:197], v[80:83]
	v_mfma_f32_16x16x32_bf16 v[76:79], v[186:189], v[198:201], v[76:79]
	v_mfma_f32_16x16x32_bf16 v[72:75], v[190:193], v[198:201], v[72:75]
	v_mfma_f32_16x16x32_bf16 v[68:71], v[202:205], v[198:201], v[68:71]
	v_mfma_f32_16x16x32_bf16 v[64:67], v[206:209], v[198:201], v[64:67]
	s_setprio 0
	s_min_u32 s6, s11, 0x380
	s_lshl_b32 s6, s6, 1
	s_waitcnt vmcnt(5)
	ds_write_b128 v158, v[124:127] offset:24576
	s_waitcnt vmcnt(4)
	ds_write_b128 v158, v[132:135] offset:28672
	v_lshl_add_u64 v[124:125], v[150:151], 0, s[6:7]
	v_lshl_add_u64 v[126:127], v[152:153], 0, s[6:7]
	v_lshl_add_u64 v[132:133], v[146:147], 0, s[6:7]
	v_lshl_add_u64 v[134:135], v[148:149], 0, s[6:7]
	ds_write_b128 v158, v[128:131] offset:8192
	s_waitcnt vmcnt(4)
	ds_write_b128 v158, v[136:139] offset:12288
	s_waitcnt lgkmcnt(0)
	s_barrier
	global_load_dwordx4 v[128:131], v[124:125], off offset:192
	global_load_dwordx4 v[136:139], v[126:127], off offset:192
	ds_read_b128 v[178:181], v161
	global_load_dwordx4 v[124:127], v[132:133], off offset:192
	ds_read_b128 v[182:185], v160 offset:24576
	global_load_dwordx4 v[132:135], v[134:135], off offset:192
	ds_read_b128 v[186:189], v161 offset:1024
	ds_read_b128 v[190:193], v160 offset:25600
	ds_read_b128 v[194:197], v161 offset:2048
	ds_read_b128 v[198:201], v160 offset:26624
	ds_read_b128 v[202:205], v161 offset:3072
	ds_read_b128 v[206:209], v160 offset:27648
	s_setprio 1
	s_waitcnt lgkmcnt(6)
	v_mfma_f32_16x16x32_bf16 v[140:143], v[182:185], v[178:181], v[140:143]
	s_waitcnt lgkmcnt(4)
	v_mfma_f32_16x16x32_bf16 v[120:123], v[190:193], v[178:181], v[120:123]
	s_waitcnt lgkmcnt(2)
	v_mfma_f32_16x16x32_bf16 v[116:119], v[198:201], v[178:181], v[116:119]
	s_waitcnt lgkmcnt(0)
	v_mfma_f32_16x16x32_bf16 v[112:115], v[206:209], v[178:181], v[112:115]
	v_mfma_f32_16x16x32_bf16 v[108:111], v[182:185], v[186:189], v[108:111]
	v_mfma_f32_16x16x32_bf16 v[104:107], v[190:193], v[186:189], v[104:107]
	v_mfma_f32_16x16x32_bf16 v[100:103], v[198:201], v[186:189], v[100:103]
	v_mfma_f32_16x16x32_bf16 v[96:99], v[206:209], v[186:189], v[96:99]
	v_mfma_f32_16x16x32_bf16 v[92:95], v[182:185], v[194:197], v[92:95]
	v_mfma_f32_16x16x32_bf16 v[88:91], v[190:193], v[194:197], v[88:91]
	v_mfma_f32_16x16x32_bf16 v[84:87], v[198:201], v[194:197], v[84:87]
	v_mfma_f32_16x16x32_bf16 v[80:83], v[206:209], v[194:197], v[80:83]
	v_mfma_f32_16x16x32_bf16 v[76:79], v[182:185], v[202:205], v[76:79]
	v_mfma_f32_16x16x32_bf16 v[72:75], v[190:193], v[202:205], v[72:75]
	v_mfma_f32_16x16x32_bf16 v[68:71], v[198:201], v[202:205], v[68:71]
	v_mfma_f32_16x16x32_bf16 v[64:67], v[206:209], v[202:205], v[64:67]
	s_setprio 0
	s_add_i32 s9, s9, 2
	s_cmp_lt_u32 s9, 30
	s_mov_b32 s11, s22
	s_waitcnt vmcnt(7)
	ds_write_b128 v158, v[162:165]
	s_waitcnt vmcnt(6)
	ds_write_b128 v159, v[166:169]
	s_waitcnt vmcnt(5)
	ds_write_b128 v158, v[170:173] offset:16384
	s_waitcnt vmcnt(4)
	ds_write_b128 v159, v[174:177] offset:16384
	s_waitcnt lgkmcnt(0)
	s_cbranch_scc1 .Lrot2_0
	s_barrier
	s_waitcnt vmcnt(3)
	v_mov_b32_e32 v128, v220
	s_waitcnt vmcnt(1)
	v_ashrrev_i32_e32 v124, 1, v128
	v_and_b32_e32 v124, 0xffffffc0, v124
	v_add_u32_e32 v124, s10, v124
	v_and_or_b32 v124, v128, 15, v124
	v_ashrrev_i32_e32 v125, 31, v124
	v_lshl_add_u64 v[126:127], v[124:125], 2, s[0:1]
	global_load_dword v144, v[126:127], off
	v_and_b32_e32 v126, 64, v128
	v_lshrrev_b32_e32 v127, 2, v128
	v_or_b32_e32 v128, 16, v124
	v_ashrrev_i32_e32 v129, 31, v128
	v_lshl_add_u64 v[136:137], v[128:129], 2, s[0:1]
	global_load_dword v156, v[136:137], off
	v_or_b32_e32 v130, 32, v124
	v_ashrrev_i32_e32 v131, 31, v130
	v_lshlrev_b64 v[152:153], 12, v[128:129]
	v_lshl_add_u64 v[128:129], v[130:131], 2, s[0:1]
	global_load_dword v157, v[128:129], off
	s_waitcnt vmcnt(3)
	v_or_b32_e32 v132, 48, v124
	v_ashrrev_i32_e32 v133, 31, v132
	v_lshlrev_b64 v[150:151], 12, v[130:131]
	v_lshl_add_u64 v[130:131], v[132:133], 2, s[0:1]
	v_and_b32_e32 v127, 12, v127
	v_or3_b32 v126, v126, v127, s8
	v_ashrrev_i32_e32 v127, 31, v126
	v_lshlrev_b64 v[134:135], 2, v[126:127]
	v_lshl_add_u64 v[138:139], s[70:71], 0, v[134:135]
	v_lshlrev_b64 v[124:125], 12, v[124:125]
	v_lshlrev_b64 v[146:147], 12, v[132:133]
	v_lshl_add_u64 v[126:127], v[138:139], 0, v[124:125]
	v_lshl_add_u64 v[132:133], v[138:139], 0, v[152:153]
	v_lshl_add_u64 v[136:137], v[138:139], 0, v[150:151]
	v_lshl_add_u64 v[148:149], v[138:139], 0, v[146:147]
	v_lshl_add_u64 v[124:125], s[70:71], 0, v[124:125]
	v_lshl_add_u64 v[124:125], v[124:125], 0, v[134:135]
	global_load_dwordx4 v[160:163], v[148:149], off offset:128
	global_load_dwordx4 v[164:167], v[136:137], off
	global_load_dwordx4 v[168:171], v[136:137], off offset:64
	global_load_dwordx4 v[172:175], v[136:137], off offset:128
	global_load_dwordx4 v[176:179], v[132:133], off
	global_load_dwordx4 v[180:183], v[132:133], off offset:128
	global_load_dwordx4 v[184:187], v[132:133], off offset:192
	global_load_dwordx4 v[188:191], v[126:127], off
	global_load_dwordx4 v[192:195], v[126:127], off offset:64
	global_load_dwordx4 v[196:199], v[126:127], off offset:128
	global_load_dwordx4 v[200:203], v[126:127], off offset:192
	s_waitcnt vmcnt(13)
	v_fmamk_f32 v128, v144, 0x3a800000, v154
	global_load_dword v144, v[130:131], off
	v_mul_f32_e32 v129, 0x4b800000, v128
	v_cmp_gt_f32_e32 vcc, s20, v128
	s_waitcnt vmcnt(0)
	v_fmamk_f32 v144, v144, 0x3a800000, v154
	v_cndmask_b32_e32 v128, v128, v129, vcc
	v_rsq_f32_e32 v128, v128
	s_nop 0
	v_mul_f32_e32 v129, 0x45800000, v128
	v_cndmask_b32_e32 v138, v128, v129, vcc
	v_mul_f32_e32 v128, v140, v138
	v_mul_f32_e32 v129, v141, v138
	v_mul_f32_e32 v130, v142, v138
	v_mul_f32_e32 v131, v143, v138
	v_mul_f32_e32 v119, v119, v138
	v_mul_f32_e32 v139, v112, v138
	v_mul_f32_e32 v112, 0xbfb8aa3b, v128
	v_mul_f32_e32 v128, 0xbfb8aa3b, v129
	v_mul_f32_e32 v129, 0xbfb8aa3b, v130
	v_mul_f32_e32 v130, 0xbfb8aa3b, v131
	v_mul_f32_e32 v119, 0xbfb8aa3b, v119
	v_exp_f32_e32 v130, v130
	v_exp_f32_e32 v119, v119
	v_mul_f32_e32 v120, v120, v138
	v_mul_f32_e32 v121, v121, v138
	v_mul_f32_e32 v122, v122, v138
	v_mul_f32_e32 v123, v123, v138
	v_mul_f32_e32 v116, v116, v138
	v_mul_f32_e32 v117, v117, v138
	v_mul_f32_e32 v118, v118, v138
	v_add_f32_e32 v130, 1.0, v130
	v_mul_f32_e32 v113, v113, v138
	v_mul_f32_e32 v114, v114, v138
	v_mul_f32_e32 v115, v115, v138
	v_fmamk_f32 v138, v156, 0x3a800000, v154
	v_add_f32_e32 v142, 1.0, v119
	v_rcp_f32_e32 v119, v130
	v_mul_f32_e32 v130, 0xbfb8aa3b, v139
	v_mul_f32_e32 v139, 0x4b800000, v138
	v_cmp_gt_f32_e32 vcc, s20, v138
	v_mul_f32_e32 v117, 0xbfb8aa3b, v117
	v_mul_f32_e32 v118, 0xbfb8aa3b, v118
	v_cndmask_b32_e32 v138, v138, v139, vcc
	v_exp_f32_e32 v129, v129
	v_exp_f32_e32 v117, v117
	v_rsq_f32_e32 v138, v138
	v_exp_f32_e32 v118, v118
	v_mul_f32_e32 v116, 0xbfb8aa3b, v116
	v_exp_f32_e32 v112, v112
	v_exp_f32_e32 v116, v116
	v_add_f32_e32 v129, 1.0, v129
	v_add_f32_e32 v140, 1.0, v117
	v_mul_f32_e32 v139, 0x45800000, v138
	v_add_f32_e32 v141, 1.0, v118
	v_rcp_f32_e32 v118, v129
	v_rcp_f32_e32 v129, v140
	v_cndmask_b32_e32 v140, v138, v139, vcc
	v_mul_f32_e32 v104, v104, v140
	v_add_f32_e32 v112, 1.0, v112
	v_mul_f32_e32 v104, 0xbfb8aa3b, v104
	v_add_f32_e32 v131, 1.0, v116
	v_rcp_f32_e32 v116, v112
	v_rcp_f32_e32 v112, v141
	v_mul_f32_e32 v108, v108, v140
	v_mul_f32_e32 v109, v109, v140
	v_mul_f32_e32 v110, v110, v140
	v_mul_f32_e32 v111, v111, v140
	v_exp_f32_e32 v141, v104
	v_mul_f32_e32 v104, v105, v140
	v_mul_f32_e32 v106, v106, v140
	v_mul_f32_e32 v107, v107, v140
	v_mul_f32_e32 v100, v100, v140
	v_mul_f32_e32 v101, v101, v140
	v_mul_f32_e32 v102, v102, v140
	v_mul_f32_e32 v103, v103, v140
	v_mul_f32_e32 v96, v96, v140
	v_mul_f32_e32 v97, v97, v140
	v_mul_f32_e32 v98, v98, v140
	v_mul_f32_e32 v99, v99, v140
	v_fmamk_f32 v140, v157, 0x3a800000, v154
	global_load_dwordx4 v[156:159], v[148:149], off
	v_exp_f32_e32 v128, v128
	v_mul_f32_e32 v113, 0xbfb8aa3b, v113
	v_lshl_add_u64 v[138:139], s[70:71], 0, v[152:153]
	v_mul_f32_e32 v104, 0xbfb8aa3b, v104
	v_add_f32_e32 v128, 1.0, v128
	v_rcp_f32_e32 v117, v128
	v_rcp_f32_e32 v128, v131
	v_exp_f32_e32 v131, v113
	v_rcp_f32_e32 v113, v142
	v_exp_f32_e32 v142, v104
	v_lshl_add_u64 v[104:105], v[138:139], 0, v[134:135]
	v_add_f32_e32 v138, 1.0, v141
	v_mul_f32_e32 v141, 0x4b800000, v140
	v_cmp_gt_f32_e32 vcc, s20, v140
	v_add_f32_e32 v139, 1.0, v142
	v_mul_f32_e32 v120, 0xbfb8aa3b, v120
	v_cndmask_b32_e32 v140, v140, v141, vcc
	v_rsq_f32_e32 v140, v140
	v_mul_f32_e32 v121, 0xbfb8aa3b, v121
	v_mul_f32_e32 v122, 0xbfb8aa3b, v122
	v_mul_f32_e32 v123, 0xbfb8aa3b, v123
	v_mul_f32_e32 v141, 0x45800000, v140
	v_cndmask_b32_e32 v152, v140, v141, vcc
	v_mul_f32_e32 v84, v84, v152
	v_mul_f32_e32 v88, v88, v152
	v_mul_f32_e32 v84, 0xbfb8aa3b, v84
	v_mul_f32_e32 v85, v85, v152
	v_mul_f32_e32 v88, 0xbfb8aa3b, v88
	v_exp_f32_e32 v84, v84
	v_mul_f32_e32 v85, 0xbfb8aa3b, v85
	v_exp_f32_e32 v142, v88
	v_exp_f32_e32 v85, v85
	v_mul_f32_e32 v88, v89, v152
	v_lshl_add_u64 v[140:141], s[70:71], 0, v[150:151]
	v_mul_f32_e32 v88, 0xbfb8aa3b, v88
	v_add_f32_e32 v84, 1.0, v84
	v_mul_f32_e32 v92, v92, v152
	v_mul_f32_e32 v93, v93, v152
	v_mul_f32_e32 v94, v94, v152
	v_mul_f32_e32 v95, v95, v152
	v_exp_f32_e32 v143, v88
	v_lshl_add_u64 v[88:89], v[140:141], 0, v[134:135]
	v_add_f32_e32 v140, 1.0, v142
	v_mul_f32_e32 v90, v90, v152
	v_mul_f32_e32 v91, v91, v152
	v_rcp_f32_e32 v142, v84
	v_add_f32_e32 v84, 1.0, v85
	v_mul_f32_e32 v85, v86, v152
	v_mul_f32_e32 v86, v87, v152
	v_mul_f32_e32 v80, v80, v152
	v_mul_f32_e32 v81, v81, v152
	v_mul_f32_e32 v82, v82, v152
	v_mul_f32_e32 v83, v83, v152
	v_mul_f32_e32 v152, 0x4b800000, v144
	v_cmp_gt_f32_e32 vcc, s20, v144
	v_mul_f32_e32 v85, 0xbfb8aa3b, v85
	v_exp_f32_e32 v85, v85
	v_cndmask_b32_e32 v144, v144, v152, vcc
	v_rsq_f32_e32 v144, v144
	v_mul_f32_e32 v86, 0xbfb8aa3b, v86
	v_exp_f32_e32 v86, v86
	v_add_f32_e32 v141, 1.0, v143
	v_mul_f32_e32 v152, 0x45800000, v144
	v_cndmask_b32_e32 v144, v144, v152, vcc
	v_mul_f32_e32 v76, v76, v144
	v_mul_f32_e32 v76, 0xbfb8aa3b, v76
	v_mul_f32_e32 v77, v77, v144
	v_exp_f32_e32 v76, v76
	v_mul_f32_e32 v77, 0xbfb8aa3b, v77
	v_exp_f32_e32 v77, v77
	v_rcp_f32_e32 v143, v84
	v_add_f32_e32 v76, 1.0, v76
	v_rcp_f32_e32 v152, v76
	v_add_f32_e32 v76, 1.0, v77
	v_mul_f32_e32 v77, v78, v144
	v_mul_f32_e32 v77, 0xbfb8aa3b, v77
	v_mul_f32_e32 v78, v79, v144
	v_exp_f32_e32 v77, v77
	v_mul_f32_e32 v78, 0xbfb8aa3b, v78
	v_exp_f32_e32 v79, v78
	v_rcp_f32_e32 v153, v76
	v_add_f32_e32 v76, 1.0, v77
	v_rcp_f32_e32 v78, v76
	v_add_f32_e32 v76, 1.0, v79
	v_rcp_f32_e32 v79, v76
	v_add_f32_e32 v84, 1.0, v85
	v_rcp_f32_e32 v150, v84
	v_add_f32_e32 v84, 1.0, v86
	v_lshl_add_u64 v[76:77], s[70:71], 0, v[146:147]
	v_rcp_f32_e32 v151, v84
	global_load_dwordx4 v[84:87], v[148:149], off offset:64
	v_lshl_add_u64 v[76:77], v[76:77], 0, v[134:135]
	global_load_dwordx4 v[146:149], v[148:149], off offset:192
	s_waitcnt vmcnt(2)
	v_pk_fma_f32 v[60:61], v[60:61], v[152:153], v[156:157]
	global_load_dwordx4 v[134:137], v[136:137], off offset:192
	v_pk_fma_f32 v[62:63], v[62:63], v[78:79], v[158:159]
	global_load_dwordx4 v[156:159], v[132:133], off offset:64
	v_mul_f32_e32 v72, v72, v144
	v_mul_f32_e32 v73, v73, v144
	v_mul_f32_e32 v74, v74, v144
	v_mul_f32_e32 v75, v75, v144
	v_mul_f32_e32 v68, v68, v144
	v_mul_f32_e32 v69, v69, v144
	v_mul_f32_e32 v70, v70, v144
	v_mul_f32_e32 v71, v71, v144
	v_mul_f32_e32 v64, v64, v144
	v_mul_f32_e32 v65, v65, v144
	v_mul_f32_e32 v66, v66, v144
	v_mul_f32_e32 v67, v67, v144
	v_mul_f32_e32 v114, 0xbfb8aa3b, v114
	v_mul_f32_e32 v115, 0xbfb8aa3b, v115
	v_mul_f32_e32 v108, 0xbfb8aa3b, v108
	v_mul_f32_e32 v109, 0xbfb8aa3b, v109
	v_mul_f32_e32 v110, 0xbfb8aa3b, v110
	v_mul_f32_e32 v111, 0xbfb8aa3b, v111
	v_mul_f32_e32 v106, 0xbfb8aa3b, v106
	v_mul_f32_e32 v107, 0xbfb8aa3b, v107
	v_mul_f32_e32 v100, 0xbfb8aa3b, v100
	v_mul_f32_e32 v101, 0xbfb8aa3b, v101
	v_mul_f32_e32 v102, 0xbfb8aa3b, v102
	v_mul_f32_e32 v103, 0xbfb8aa3b, v103
	v_mul_f32_e32 v96, 0xbfb8aa3b, v96
	v_mul_f32_e32 v97, 0xbfb8aa3b, v97
	v_mul_f32_e32 v98, 0xbfb8aa3b, v98
	v_mul_f32_e32 v99, 0xbfb8aa3b, v99
	v_mul_f32_e32 v92, 0xbfb8aa3b, v92
	v_mul_f32_e32 v93, 0xbfb8aa3b, v93
	v_mul_f32_e32 v94, 0xbfb8aa3b, v94
	v_mul_f32_e32 v95, 0xbfb8aa3b, v95
	v_mul_f32_e32 v90, 0xbfb8aa3b, v90
	v_mul_f32_e32 v91, 0xbfb8aa3b, v91
	v_mul_f32_e32 v80, 0xbfb8aa3b, v80
	v_mul_f32_e32 v81, 0xbfb8aa3b, v81
	v_mul_f32_e32 v82, 0xbfb8aa3b, v82
	v_mul_f32_e32 v83, 0xbfb8aa3b, v83
	v_mul_f32_e32 v72, 0xbfb8aa3b, v72
	v_mul_f32_e32 v73, 0xbfb8aa3b, v73
	v_mul_f32_e32 v74, 0xbfb8aa3b, v74
	v_mul_f32_e32 v75, 0xbfb8aa3b, v75
	v_mul_f32_e32 v68, 0xbfb8aa3b, v68
	v_mul_f32_e32 v69, 0xbfb8aa3b, v69
	v_mul_f32_e32 v70, 0xbfb8aa3b, v70
	v_mul_f32_e32 v71, 0xbfb8aa3b, v71
	v_mul_f32_e32 v64, 0xbfb8aa3b, v64
	v_mul_f32_e32 v65, 0xbfb8aa3b, v65
	v_mul_f32_e32 v66, 0xbfb8aa3b, v66
	v_mul_f32_e32 v67, 0xbfb8aa3b, v67
	v_exp_f32_e32 v120, v120
	v_exp_f32_e32 v121, v121
	v_exp_f32_e32 v122, v122
	v_exp_f32_e32 v123, v123
	v_exp_f32_e32 v130, v130
	v_exp_f32_e32 v114, v114
	v_exp_f32_e32 v115, v115
	v_exp_f32_e32 v108, v108
	v_exp_f32_e32 v109, v109
	v_exp_f32_e32 v110, v110
	v_exp_f32_e32 v111, v111
	v_exp_f32_e32 v106, v106
	v_exp_f32_e32 v107, v107
	v_exp_f32_e32 v100, v100
	v_exp_f32_e32 v101, v101
	v_exp_f32_e32 v102, v102
	v_exp_f32_e32 v103, v103
	v_exp_f32_e32 v96, v96
	v_exp_f32_e32 v97, v97
	v_exp_f32_e32 v98, v98
	v_exp_f32_e32 v99, v99
	v_exp_f32_e32 v92, v92
	v_exp_f32_e32 v93, v93
	v_exp_f32_e32 v94, v94
	v_exp_f32_e32 v95, v95
	v_exp_f32_e32 v90, v90
	v_exp_f32_e32 v91, v91
	v_exp_f32_e32 v80, v80
	v_exp_f32_e32 v81, v81
	v_exp_f32_e32 v82, v82
	v_exp_f32_e32 v83, v83
	v_exp_f32_e32 v72, v72
	v_exp_f32_e32 v73, v73
	v_exp_f32_e32 v74, v74
	v_exp_f32_e32 v75, v75
	v_exp_f32_e32 v68, v68
	v_exp_f32_e32 v69, v69
	v_exp_f32_e32 v70, v70
	v_exp_f32_e32 v71, v71
	v_exp_f32_e32 v64, v64
	v_exp_f32_e32 v65, v65
	v_exp_f32_e32 v66, v66
	v_exp_f32_e32 v67, v67
	v_add_f32_e32 v120, 1.0, v120
	v_add_f32_e32 v121, 1.0, v121
	v_add_f32_e32 v122, 1.0, v122
	v_add_f32_e32 v123, 1.0, v123
	v_add_f32_e32 v130, 1.0, v130
	v_add_f32_e32 v131, 1.0, v131
	v_add_f32_e32 v114, 1.0, v114
	v_add_f32_e32 v115, 1.0, v115
	v_add_f32_e32 v108, 1.0, v108
	v_add_f32_e32 v109, 1.0, v109
	v_add_f32_e32 v110, 1.0, v110
	v_add_f32_e32 v111, 1.0, v111
	v_add_f32_e32 v106, 1.0, v106
	v_add_f32_e32 v107, 1.0, v107
	v_add_f32_e32 v100, 1.0, v100
	v_add_f32_e32 v101, 1.0, v101
	v_add_f32_e32 v102, 1.0, v102
	v_add_f32_e32 v103, 1.0, v103
	v_add_f32_e32 v96, 1.0, v96
	v_add_f32_e32 v97, 1.0, v97
	v_add_f32_e32 v98, 1.0, v98
	v_add_f32_e32 v99, 1.0, v99
	v_add_f32_e32 v92, 1.0, v92
	v_add_f32_e32 v93, 1.0, v93
	v_add_f32_e32 v94, 1.0, v94
	v_add_f32_e32 v95, 1.0, v95
	v_add_f32_e32 v90, 1.0, v90
	v_add_f32_e32 v91, 1.0, v91
	v_add_f32_e32 v80, 1.0, v80
	v_add_f32_e32 v81, 1.0, v81
	v_add_f32_e32 v82, 1.0, v82
	v_add_f32_e32 v83, 1.0, v83
	v_add_f32_e32 v72, 1.0, v72
	v_add_f32_e32 v73, 1.0, v73
	v_add_f32_e32 v74, 1.0, v74
	v_add_f32_e32 v75, 1.0, v75
	v_add_f32_e32 v68, 1.0, v68
	v_add_f32_e32 v69, 1.0, v69
	v_add_f32_e32 v70, 1.0, v70
	v_add_f32_e32 v71, 1.0, v71
	v_add_f32_e32 v64, 1.0, v64
	v_add_f32_e32 v65, 1.0, v65
	v_add_f32_e32 v66, 1.0, v66
	v_add_f32_e32 v67, 1.0, v67
	v_rcp_f32_e32 v120, v120
	v_rcp_f32_e32 v121, v121
	v_rcp_f32_e32 v122, v122
	v_rcp_f32_e32 v123, v123
	v_rcp_f32_e32 v130, v130
	v_rcp_f32_e32 v131, v131
	v_rcp_f32_e32 v114, v114
	v_rcp_f32_e32 v115, v115
	v_rcp_f32_e32 v108, v108
	v_rcp_f32_e32 v109, v109
	v_rcp_f32_e32 v110, v110
	v_rcp_f32_e32 v111, v111
	v_rcp_f32_e32 v138, v138
	v_rcp_f32_e32 v139, v139
	v_rcp_f32_e32 v106, v106
	v_rcp_f32_e32 v107, v107
	v_rcp_f32_e32 v100, v100
	v_rcp_f32_e32 v101, v101
	v_rcp_f32_e32 v102, v102
	v_rcp_f32_e32 v103, v103
	v_rcp_f32_e32 v96, v96
	v_rcp_f32_e32 v97, v97
	v_rcp_f32_e32 v98, v98
	v_rcp_f32_e32 v99, v99
	v_rcp_f32_e32 v92, v92
	v_rcp_f32_e32 v93, v93
	v_rcp_f32_e32 v94, v94
	v_rcp_f32_e32 v95, v95
	v_rcp_f32_e32 v140, v140
	v_rcp_f32_e32 v141, v141
	v_rcp_f32_e32 v90, v90
	v_rcp_f32_e32 v91, v91
	v_rcp_f32_e32 v80, v80
	v_rcp_f32_e32 v81, v81
	v_rcp_f32_e32 v82, v82
	v_rcp_f32_e32 v83, v83
	v_rcp_f32_e32 v72, v72
	v_rcp_f32_e32 v73, v73
	v_rcp_f32_e32 v74, v74
	v_rcp_f32_e32 v75, v75
	v_rcp_f32_e32 v68, v68
	v_rcp_f32_e32 v69, v69
	v_rcp_f32_e32 v70, v70
	v_rcp_f32_e32 v71, v71
	v_rcp_f32_e32 v64, v64
	v_rcp_f32_e32 v65, v65
	v_rcp_f32_e32 v66, v66
	v_rcp_f32_e32 v67, v67
	s_waitcnt vmcnt(3)
	v_pk_fma_f32 v[56:57], v[56:57], v[72:73], v[84:85]
	v_pk_fma_f32 v[58:59], v[58:59], v[74:75], v[86:87]
	v_pk_fma_f32 v[4:5], v[4:5], v[68:69], v[160:161]
	v_pk_fma_f32 v[6:7], v[6:7], v[70:71], v[162:163]
	s_waitcnt vmcnt(2)
	v_pk_fma_f32 v[0:1], v[0:1], v[64:65], v[146:147]
	v_pk_fma_f32 v[2:3], v[2:3], v[66:67], v[148:149]
	v_pk_fma_f32 v[32:33], v[32:33], v[92:93], v[164:165]
	v_pk_fma_f32 v[34:35], v[34:35], v[94:95], v[166:167]
	v_pk_fma_f32 v[24:25], v[24:25], v[140:141], v[168:169]
	v_pk_fma_f32 v[26:27], v[26:27], v[90:91], v[170:171]
	v_pk_fma_f32 v[12:13], v[12:13], v[142:143], v[172:173]
	v_pk_fma_f32 v[14:15], v[14:15], v[150:151], v[174:175]
	s_waitcnt vmcnt(1)
	v_pk_fma_f32 v[8:9], v[8:9], v[80:81], v[134:135]
	v_pk_fma_f32 v[10:11], v[10:11], v[82:83], v[136:137]
	v_pk_fma_f32 v[44:45], v[44:45], v[108:109], v[176:177]
	v_pk_fma_f32 v[46:47], v[46:47], v[110:111], v[178:179]
	s_waitcnt vmcnt(0)
	v_pk_fma_f32 v[36:37], v[36:37], v[138:139], v[156:157]
	v_pk_fma_f32 v[38:39], v[38:39], v[106:107], v[158:159]
	v_pk_fma_f32 v[28:29], v[28:29], v[100:101], v[180:181]
	v_pk_fma_f32 v[30:31], v[30:31], v[102:103], v[182:183]
	v_pk_fma_f32 v[16:17], v[16:17], v[96:97], v[184:185]
	v_pk_fma_f32 v[18:19], v[18:19], v[98:99], v[186:187]
	v_pk_fma_f32 v[52:53], v[52:53], v[116:117], v[188:189]
	v_pk_fma_f32 v[54:55], v[54:55], v[118:119], v[190:191]
	v_pk_fma_f32 v[48:49], v[48:49], v[120:121], v[192:193]
	v_pk_fma_f32 v[50:51], v[50:51], v[122:123], v[194:195]
	v_pk_fma_f32 v[40:41], v[40:41], v[128:129], v[196:197]
	v_pk_fma_f32 v[42:43], v[42:43], v[112:113], v[198:199]
	v_pk_fma_f32 v[20:21], v[20:21], v[130:131], v[200:201]
	v_pk_fma_f32 v[22:23], v[22:23], v[114:115], v[202:203]
	s_add_i32 s21, s21, s74
	s_cmpk_lt_i32 s21, 0x800
	global_store_dwordx4 v[124:125], v[52:55], off
	global_store_dwordx4 v[124:125], v[48:51], off offset:64
	global_store_dwordx4 v[124:125], v[40:43], off offset:128
	global_store_dwordx4 v[124:125], v[20:23], off offset:192
	global_store_dwordx4 v[104:105], v[44:47], off
	global_store_dwordx4 v[104:105], v[36:39], off offset:64
	global_store_dwordx4 v[104:105], v[28:31], off offset:128
	global_store_dwordx4 v[104:105], v[16:19], off offset:192
	global_store_dwordx4 v[88:89], v[32:35], off
	global_store_dwordx4 v[88:89], v[24:27], off offset:64
	global_store_dwordx4 v[88:89], v[12:15], off offset:128
	global_store_dwordx4 v[88:89], v[8:11], off offset:192
	global_store_dwordx4 v[76:77], v[60:63], off
	global_store_dwordx4 v[76:77], v[56:59], off offset:64
	global_store_dwordx4 v[76:77], v[4:7], off offset:128
	global_store_dwordx4 v[76:77], v[0:3], off offset:192
	s_cbranch_scc1 .LBB0_1866
